# duplicate lgkmcnt(0) waits in front of / inside the MFMA runs removed (38), MFMA runs re-padded
# speedup vs baseline: 1.0172x; 1.0172x over previous
.LBB0_103:
	s_ashr_i32 s23, s22, 31
	s_lshl_b64 s[2:3], s[22:23], 19
	s_add_u32 s58, s90, s2
	s_addc_u32 s59, s77, s3
	s_and_b64 s[2:3], s[46:47], exec
	s_cselect_b32 s1, s59, s49
	s_cselect_b32 s23, s58, s48
	s_add_u32 s34, s34, 0x3e080
	s_addc_u32 s35, s35, 0
	s_add_u32 s51, s48, 0x100
	v_mov_b32_e32 v2, 0
	s_addc_u32 s52, s49, 0
	s_mov_b32 s53, -2
	s_add_u32 s2, s34, 0xfffc2080
	s_addc_u32 s3, s35, -1
	s_add_i32 s12, 0, 0x10000
	v_add_u32_e32 v110, s12, v179
	ds_read_b128 v[98:101], v110
	ds_read_b128 v[102:105], v110 offset:1024
	ds_read_b128 v[106:109], v110 offset:2048
	ds_read_b128 v[110:113], v110 offset:3072
	s_cmp_eq_u32 s53, 12
	s_cselect_b32 s49, s97, s3
	s_cselect_b32 s48, s96, s2
	s_cselect_b32 s3, s1, s52
	s_cselect_b32 s2, s23, s51
	v_lshl_add_u64 v[174:175], s[34:35], 0, v[170:171]
	s_add_i32 m0, s85, 0xc000
	ds_read_b128 v[114:117], v184
	ds_read_b128 v[118:121], v184 offset:1024
	ds_read_b128 v[122:125], v184 offset:2048
	ds_read_b128 v[126:129], v184 offset:3072
	ds_read_b128 v[186:189], v184 offset:4096
	ds_read_b128 v[190:193], v184 offset:5120
	ds_read_b128 v[194:197], v184 offset:6144
	ds_read_b128 v[198:201], v184 offset:7168
	global_load_lds_dwordx4 v[174:175], off
	v_lshl_add_u64 v[174:175], s[34:35], 0, v[172:173]
	s_add_i32 m0, s85, 0xe000
	s_nop 0
	global_load_lds_dwordx4 v[174:175], off
	s_waitcnt lgkmcnt(8)
	s_add_i32 s54, 0, 0x14000
	v_add_u32_e32 v174, s54, v179
	s_add_i32 s12, s12, s78
	ds_read_b128 v[226:229], v174
	ds_read_b128 v[230:233], v174 offset:1024
	ds_read_b128 v[234:237], v174 offset:2048
	ds_read_b128 v[242:245], v174 offset:3072
	s_barrier
	s_waitcnt lgkmcnt(0)
	v_mfma_f32_16x16x32_bf16 v[158:161], v[98:101], v[114:117], 0
	v_mfma_f32_16x16x32_bf16 v[154:157], v[106:109], v[114:117], 0
	v_mfma_f32_16x16x32_bf16 v[150:153], v[98:101], v[122:125], 0
	v_mfma_f32_16x16x32_bf16 v[146:149], v[106:109], v[122:125], 0
	v_mfma_f32_16x16x32_bf16 v[142:145], v[98:101], v[186:189], 0
	v_mfma_f32_16x16x32_bf16 v[138:141], v[106:109], v[186:189], 0
	v_mfma_f32_16x16x32_bf16 v[134:137], v[98:101], v[194:197], 0
	v_mfma_f32_16x16x32_bf16 v[130:133], v[106:109], v[194:197], 0
	v_mfma_f32_16x16x32_bf16 v[158:161], v[102:105], v[118:121], v[158:161]
	v_mfma_f32_16x16x32_bf16 v[154:157], v[110:113], v[118:121], v[154:157]
	v_mfma_f32_16x16x32_bf16 v[150:153], v[102:105], v[126:129], v[150:153]
	v_mfma_f32_16x16x32_bf16 v[146:149], v[110:113], v[126:129], v[146:149]
	v_mfma_f32_16x16x32_bf16 v[142:145], v[102:105], v[190:193], v[142:145]
	v_mfma_f32_16x16x32_bf16 v[138:141], v[110:113], v[190:193], v[138:141]
	v_mfma_f32_16x16x32_bf16 v[134:137], v[102:105], v[198:201], v[134:137]
	v_mfma_f32_16x16x32_bf16 v[130:133], v[110:113], v[198:201], v[130:133]
	v_mfma_f32_16x16x32_bf16 v[62:65], v[226:229], v[114:117], 0
	v_mfma_f32_16x16x32_bf16 v[58:61], v[234:237], v[114:117], 0
	v_mfma_f32_16x16x32_bf16 v[54:57], v[226:229], v[122:125], 0
	v_mfma_f32_16x16x32_bf16 v[50:53], v[234:237], v[122:125], 0
	v_mfma_f32_16x16x32_bf16 v[46:49], v[226:229], v[186:189], 0
	v_mfma_f32_16x16x32_bf16 v[42:45], v[234:237], v[186:189], 0
	v_mfma_f32_16x16x32_bf16 v[38:41], v[226:229], v[194:197], 0
	v_mfma_f32_16x16x32_bf16 v[34:37], v[234:237], v[194:197], 0
	v_mfma_f32_16x16x32_bf16 v[62:65], v[230:233], v[118:121], v[62:65]
	v_mfma_f32_16x16x32_bf16 v[58:61], v[242:245], v[118:121], v[58:61]
	v_mfma_f32_16x16x32_bf16 v[54:57], v[230:233], v[126:129], v[54:57]
	v_mfma_f32_16x16x32_bf16 v[50:53], v[242:245], v[126:129], v[50:53]
	v_mfma_f32_16x16x32_bf16 v[46:49], v[230:233], v[190:193], v[46:49]
	v_mfma_f32_16x16x32_bf16 v[42:45], v[242:245], v[190:193], v[42:45]
	v_mfma_f32_16x16x32_bf16 v[38:41], v[230:233], v[198:201], v[38:41]
	v_mfma_f32_16x16x32_bf16 v[34:37], v[242:245], v[198:201], v[34:37]
	s_mov_b32 m0, s85
	v_lshl_add_u64 v[248:249], s[48:49], 0, v[162:163]
	s_barrier
	ds_read_b128 v[114:117], v184 offset:16384
	ds_read_b128 v[118:121], v184 offset:17408
	ds_read_b128 v[122:125], v184 offset:18432
	ds_read_b128 v[126:129], v184 offset:19456
	ds_read_b128 v[186:189], v184 offset:20480
	ds_read_b128 v[190:193], v184 offset:21504
	ds_read_b128 v[194:197], v184 offset:22528
	ds_read_b128 v[198:201], v184 offset:23552
	global_load_lds_dwordx4 v[248:249], off
	v_lshl_add_u64 v[250:251], s[48:49], 0, v[164:165]
	s_mov_b32 m0, s82
	s_nop 0
	global_load_lds_dwordx4 v[250:251], off
	v_lshl_add_u64 v[174:175], s[2:3], 0, v[0:1]
	s_mov_b32 m0, s12
	v_lshl_add_u64 v[246:247], s[2:3], 0, v[166:167]
	global_load_lds_dwordx4 v[174:175], off
	s_add_i32 m0, s12, 0x2000
	s_nop 0
	global_load_lds_dwordx4 v[246:247], off
	s_add_u32 s12, s2, 0x40000
	s_addc_u32 s13, s3, 0
	s_add_i32 s54, s54, s78
	v_lshl_add_u64 v[174:175], s[12:13], 0, v[0:1]
	s_mov_b32 m0, s54
	s_nop 0
	global_load_lds_dwordx4 v[174:175], off
	v_lshl_add_u64 v[174:175], s[12:13], 0, v[166:167]
	s_add_i32 m0, s54, 0x2000
	s_nop 0
	global_load_lds_dwordx4 v[174:175], off
	s_waitcnt vmcnt(6)
	s_barrier
	s_waitcnt lgkmcnt(0)
	v_mfma_f32_16x16x32_bf16 v[94:97], v[98:101], v[114:117], 0
	v_mfma_f32_16x16x32_bf16 v[90:93], v[106:109], v[114:117], 0
	v_mfma_f32_16x16x32_bf16 v[86:89], v[98:101], v[122:125], 0
	v_mfma_f32_16x16x32_bf16 v[82:85], v[106:109], v[122:125], 0
	v_mfma_f32_16x16x32_bf16 v[78:81], v[98:101], v[186:189], 0
	v_mfma_f32_16x16x32_bf16 v[74:77], v[106:109], v[186:189], 0
	v_mfma_f32_16x16x32_bf16 v[70:73], v[98:101], v[194:197], 0
	v_mfma_f32_16x16x32_bf16 v[66:69], v[106:109], v[194:197], 0
	v_mfma_f32_16x16x32_bf16 v[94:97], v[102:105], v[118:121], v[94:97]
	v_mfma_f32_16x16x32_bf16 v[90:93], v[110:113], v[118:121], v[90:93]
	v_mfma_f32_16x16x32_bf16 v[86:89], v[102:105], v[126:129], v[86:89]
	v_mfma_f32_16x16x32_bf16 v[82:85], v[110:113], v[126:129], v[82:85]
	v_mfma_f32_16x16x32_bf16 v[78:81], v[102:105], v[190:193], v[78:81]
	v_mfma_f32_16x16x32_bf16 v[74:77], v[110:113], v[190:193], v[74:77]
	v_mfma_f32_16x16x32_bf16 v[70:73], v[102:105], v[198:201], v[70:73]
	v_mfma_f32_16x16x32_bf16 v[66:69], v[110:113], v[198:201], v[66:69]
	v_mfma_f32_16x16x32_bf16 v[30:33], v[226:229], v[114:117], 0
	v_mfma_f32_16x16x32_bf16 v[26:29], v[234:237], v[114:117], 0
	v_mfma_f32_16x16x32_bf16 v[22:25], v[226:229], v[122:125], 0
	v_mfma_f32_16x16x32_bf16 v[18:21], v[234:237], v[122:125], 0
	v_mfma_f32_16x16x32_bf16 v[14:17], v[226:229], v[186:189], 0
	v_mfma_f32_16x16x32_bf16 v[10:13], v[234:237], v[186:189], 0
	v_mfma_f32_16x16x32_bf16 v[6:9], v[226:229], v[194:197], 0
	v_mfma_f32_16x16x32_bf16 v[2:5], v[234:237], v[194:197], 0
	v_mfma_f32_16x16x32_bf16 v[30:33], v[230:233], v[118:121], v[30:33]
	v_mfma_f32_16x16x32_bf16 v[26:29], v[242:245], v[118:121], v[26:29]
	v_mfma_f32_16x16x32_bf16 v[22:25], v[230:233], v[126:129], v[22:25]
	v_mfma_f32_16x16x32_bf16 v[18:21], v[242:245], v[126:129], v[18:21]
	v_mfma_f32_16x16x32_bf16 v[14:17], v[230:233], v[190:193], v[14:17]
	v_mfma_f32_16x16x32_bf16 v[10:13], v[242:245], v[190:193], v[10:13]
	v_mfma_f32_16x16x32_bf16 v[6:9], v[230:233], v[198:201], v[6:9]
	v_mfma_f32_16x16x32_bf16 v[2:5], v[242:245], v[198:201], v[2:5]
	s_add_i32 s54, 0, 0x18000
	v_add_u32_e32 v110, s54, v179
	s_barrier
	ds_read_b128 v[98:101], v110
	ds_read_b128 v[102:105], v110 offset:1024
	ds_read_b128 v[106:109], v110 offset:2048
	ds_read_b128 v[110:113], v110 offset:3072
	s_add_u32 s12, s48, 0x3e000
	s_addc_u32 s13, s49, 0
	s_mov_b32 m0, s89
	v_lshl_add_u64 v[226:227], s[12:13], 0, v[162:163]
	ds_read_b128 v[114:117], v184 offset:32768
	ds_read_b128 v[118:121], v184 offset:33792
	ds_read_b128 v[122:125], v184 offset:34816
	ds_read_b128 v[126:129], v184 offset:35840
	ds_read_b128 v[186:189], v184 offset:36864
	ds_read_b128 v[190:193], v184 offset:37888
	ds_read_b128 v[194:197], v184 offset:38912
	ds_read_b128 v[198:201], v184 offset:39936
	global_load_lds_dwordx4 v[226:227], off
	v_lshl_add_u64 v[226:227], s[12:13], 0, v[164:165]
	s_mov_b32 m0, s91
	s_nop 0
	global_load_lds_dwordx4 v[226:227], off
	s_waitcnt lgkmcnt(8)
	s_add_i32 s12, 0, 0x1c000
	s_add_i32 s13, s54, s78
	v_add_u32_e32 v242, s12, v179
	ds_read_b128 v[226:229], v242
	ds_read_b128 v[230:233], v242 offset:1024
	ds_read_b128 v[234:237], v242 offset:2048
	ds_read_b128 v[242:245], v242 offset:3072
	s_barrier
	s_waitcnt lgkmcnt(0)
	s_nop 0
	v_mfma_f32_16x16x32_bf16 v[158:161], v[98:101], v[114:117], v[158:161]
	v_mfma_f32_16x16x32_bf16 v[154:157], v[106:109], v[114:117], v[154:157]
	v_mfma_f32_16x16x32_bf16 v[150:153], v[98:101], v[122:125], v[150:153]
	v_mfma_f32_16x16x32_bf16 v[146:149], v[106:109], v[122:125], v[146:149]
	v_mfma_f32_16x16x32_bf16 v[142:145], v[98:101], v[186:189], v[142:145]
	v_mfma_f32_16x16x32_bf16 v[138:141], v[106:109], v[186:189], v[138:141]
	v_mfma_f32_16x16x32_bf16 v[134:137], v[98:101], v[194:197], v[134:137]
	v_mfma_f32_16x16x32_bf16 v[130:133], v[106:109], v[194:197], v[130:133]
	v_mfma_f32_16x16x32_bf16 v[158:161], v[102:105], v[118:121], v[158:161]
	v_mfma_f32_16x16x32_bf16 v[154:157], v[110:113], v[118:121], v[154:157]
	v_mfma_f32_16x16x32_bf16 v[150:153], v[102:105], v[126:129], v[150:153]
	v_mfma_f32_16x16x32_bf16 v[146:149], v[110:113], v[126:129], v[146:149]
	v_mfma_f32_16x16x32_bf16 v[142:145], v[102:105], v[190:193], v[142:145]
	v_mfma_f32_16x16x32_bf16 v[138:141], v[110:113], v[190:193], v[138:141]
	v_mfma_f32_16x16x32_bf16 v[134:137], v[102:105], v[198:201], v[134:137]
	v_mfma_f32_16x16x32_bf16 v[130:133], v[110:113], v[198:201], v[130:133]
	v_mfma_f32_16x16x32_bf16 v[62:65], v[226:229], v[114:117], v[62:65]
	v_mfma_f32_16x16x32_bf16 v[58:61], v[234:237], v[114:117], v[58:61]
	v_mfma_f32_16x16x32_bf16 v[54:57], v[226:229], v[122:125], v[54:57]
	v_mfma_f32_16x16x32_bf16 v[50:53], v[234:237], v[122:125], v[50:53]
	v_mfma_f32_16x16x32_bf16 v[46:49], v[226:229], v[186:189], v[46:49]
	v_mfma_f32_16x16x32_bf16 v[42:45], v[234:237], v[186:189], v[42:45]
	v_mfma_f32_16x16x32_bf16 v[38:41], v[226:229], v[194:197], v[38:41]
	v_mfma_f32_16x16x32_bf16 v[34:37], v[234:237], v[194:197], v[34:37]
	v_mfma_f32_16x16x32_bf16 v[62:65], v[230:233], v[118:121], v[62:65]
	v_mfma_f32_16x16x32_bf16 v[58:61], v[242:245], v[118:121], v[58:61]
	v_mfma_f32_16x16x32_bf16 v[54:57], v[230:233], v[126:129], v[54:57]
	v_mfma_f32_16x16x32_bf16 v[50:53], v[242:245], v[126:129], v[50:53]
	v_mfma_f32_16x16x32_bf16 v[46:49], v[230:233], v[190:193], v[46:49]
	v_mfma_f32_16x16x32_bf16 v[42:45], v[242:245], v[190:193], v[42:45]
	v_mfma_f32_16x16x32_bf16 v[38:41], v[230:233], v[198:201], v[38:41]
	v_mfma_f32_16x16x32_bf16 v[34:37], v[242:245], v[198:201], v[34:37]
	s_mov_b32 m0, s79
	v_lshl_add_u64 v[174:175], v[248:249], 0, s[20:21]
	s_barrier
	ds_read_b128 v[114:117], v184 offset:49152
	ds_read_b128 v[118:121], v184 offset:50176
	ds_read_b128 v[122:125], v184 offset:51200
	ds_read_b128 v[126:129], v184 offset:52224
	ds_read_b128 v[186:189], v184 offset:53248
	ds_read_b128 v[190:193], v184 offset:54272
	ds_read_b128 v[194:197], v184 offset:55296
	ds_read_b128 v[198:201], v184 offset:56320
	global_load_lds_dwordx4 v[174:175], off
	v_lshl_add_u64 v[174:175], v[250:251], 0, s[20:21]
	s_mov_b32 m0, s87
	s_nop 0
	global_load_lds_dwordx4 v[174:175], off
	v_lshl_add_u64 v[174:175], s[2:3], 0, v[0:1]
	v_lshl_add_u64 v[174:175], v[174:175], 0, s[20:21]
	s_mov_b32 m0, s13
	s_nop 0
	global_load_lds_dwordx4 v[174:175], off
	v_lshl_add_u64 v[174:175], v[246:247], 0, s[20:21]
	s_add_i32 m0, s13, 0x2000
	s_nop 0
	global_load_lds_dwordx4 v[174:175], off
	s_add_u32 s2, s2, 0x40080
	s_addc_u32 s3, s3, 0
	s_add_i32 s12, s12, s78
	v_lshl_add_u64 v[174:175], s[2:3], 0, v[0:1]
	s_mov_b32 m0, s12
	s_nop 0
	global_load_lds_dwordx4 v[174:175], off
	v_lshl_add_u64 v[174:175], s[2:3], 0, v[166:167]
	s_add_i32 m0, s12, 0x2000
	s_nop 0
	global_load_lds_dwordx4 v[174:175], off
	s_waitcnt vmcnt(6)
	s_barrier
	s_waitcnt lgkmcnt(0)
	s_nop 0
	v_mfma_f32_16x16x32_bf16 v[94:97], v[98:101], v[114:117], v[94:97]
	v_mfma_f32_16x16x32_bf16 v[90:93], v[106:109], v[114:117], v[90:93]
	v_mfma_f32_16x16x32_bf16 v[86:89], v[98:101], v[122:125], v[86:89]
	v_mfma_f32_16x16x32_bf16 v[82:85], v[106:109], v[122:125], v[82:85]
	v_mfma_f32_16x16x32_bf16 v[78:81], v[98:101], v[186:189], v[78:81]
	v_mfma_f32_16x16x32_bf16 v[74:77], v[106:109], v[186:189], v[74:77]
	v_mfma_f32_16x16x32_bf16 v[70:73], v[98:101], v[194:197], v[70:73]
	v_mfma_f32_16x16x32_bf16 v[66:69], v[106:109], v[194:197], v[66:69]
	v_mfma_f32_16x16x32_bf16 v[94:97], v[102:105], v[118:121], v[94:97]
	v_mfma_f32_16x16x32_bf16 v[90:93], v[110:113], v[118:121], v[90:93]
	v_mfma_f32_16x16x32_bf16 v[86:89], v[102:105], v[126:129], v[86:89]
	v_mfma_f32_16x16x32_bf16 v[82:85], v[110:113], v[126:129], v[82:85]
	v_mfma_f32_16x16x32_bf16 v[78:81], v[102:105], v[190:193], v[78:81]
	v_mfma_f32_16x16x32_bf16 v[74:77], v[110:113], v[190:193], v[74:77]
	v_mfma_f32_16x16x32_bf16 v[70:73], v[102:105], v[198:201], v[70:73]
	v_mfma_f32_16x16x32_bf16 v[66:69], v[110:113], v[198:201], v[66:69]
	v_mfma_f32_16x16x32_bf16 v[30:33], v[226:229], v[114:117], v[30:33]
	v_mfma_f32_16x16x32_bf16 v[26:29], v[234:237], v[114:117], v[26:29]
	v_mfma_f32_16x16x32_bf16 v[22:25], v[226:229], v[122:125], v[22:25]
	v_mfma_f32_16x16x32_bf16 v[18:21], v[234:237], v[122:125], v[18:21]
	v_mfma_f32_16x16x32_bf16 v[14:17], v[226:229], v[186:189], v[14:17]
	v_mfma_f32_16x16x32_bf16 v[10:13], v[234:237], v[186:189], v[10:13]
	v_mfma_f32_16x16x32_bf16 v[6:9], v[226:229], v[194:197], v[6:9]
	v_mfma_f32_16x16x32_bf16 v[2:5], v[234:237], v[194:197], v[2:5]
	v_mfma_f32_16x16x32_bf16 v[30:33], v[230:233], v[118:121], v[30:33]
	v_mfma_f32_16x16x32_bf16 v[26:29], v[242:245], v[118:121], v[26:29]
	v_mfma_f32_16x16x32_bf16 v[22:25], v[230:233], v[126:129], v[22:25]
	v_mfma_f32_16x16x32_bf16 v[18:21], v[242:245], v[126:129], v[18:21]
	v_mfma_f32_16x16x32_bf16 v[14:17], v[230:233], v[190:193], v[14:17]
	v_mfma_f32_16x16x32_bf16 v[10:13], v[242:245], v[190:193], v[10:13]
	v_mfma_f32_16x16x32_bf16 v[6:9], v[230:233], v[198:201], v[6:9]
	v_mfma_f32_16x16x32_bf16 v[2:5], v[242:245], v[198:201], v[2:5]
	s_add_i32 s53, s53, 2
	s_add_u32 s34, s34, 0x100
	s_addc_u32 s35, s35, 0
	s_add_u32 s51, s51, 0x100
	s_addc_u32 s52, s52, 0
	s_cmp_gt_u32 s53, 13
	s_barrier
	s_cbranch_scc1 .Lpeel_x_0
.LBB0_104:
	s_add_u32 s2, s34, 0xfffc2080
	s_addc_u32 s3, s35, -1
	s_add_i32 s12, 0, 0x10000
	v_add_u32_e32 v110, s12, v179
	ds_read_b128 v[98:101], v110
	ds_read_b128 v[102:105], v110 offset:1024
	ds_read_b128 v[106:109], v110 offset:2048
	ds_read_b128 v[110:113], v110 offset:3072
	s_cmp_eq_u32 s53, 12
	s_cselect_b32 s49, s97, s3
	s_cselect_b32 s48, s96, s2
	s_cselect_b32 s3, s1, s52
	s_cselect_b32 s2, s23, s51
	v_lshl_add_u64 v[174:175], s[34:35], 0, v[170:171]
	s_add_i32 m0, s85, 0xc000
	ds_read_b128 v[114:117], v184
	ds_read_b128 v[118:121], v184 offset:1024
	ds_read_b128 v[122:125], v184 offset:2048
	ds_read_b128 v[126:129], v184 offset:3072
	ds_read_b128 v[186:189], v184 offset:4096
	ds_read_b128 v[190:193], v184 offset:5120
	ds_read_b128 v[194:197], v184 offset:6144
	ds_read_b128 v[198:201], v184 offset:7168
	global_load_lds_dwordx4 v[174:175], off
	v_lshl_add_u64 v[174:175], s[34:35], 0, v[172:173]
	s_add_i32 m0, s85, 0xe000
	s_nop 0
	global_load_lds_dwordx4 v[174:175], off
	s_waitcnt lgkmcnt(8)
	s_add_i32 s54, 0, 0x14000
	v_add_u32_e32 v174, s54, v179
	s_add_i32 s12, s12, s78
	ds_read_b128 v[226:229], v174
	ds_read_b128 v[230:233], v174 offset:1024
	ds_read_b128 v[234:237], v174 offset:2048
	ds_read_b128 v[242:245], v174 offset:3072
	s_barrier
	s_waitcnt lgkmcnt(0)
	s_nop 0
	v_mfma_f32_16x16x32_bf16 v[158:161], v[98:101], v[114:117], v[158:161]
	v_mfma_f32_16x16x32_bf16 v[154:157], v[106:109], v[114:117], v[154:157]
	v_mfma_f32_16x16x32_bf16 v[150:153], v[98:101], v[122:125], v[150:153]
	v_mfma_f32_16x16x32_bf16 v[146:149], v[106:109], v[122:125], v[146:149]
	v_mfma_f32_16x16x32_bf16 v[142:145], v[98:101], v[186:189], v[142:145]
	v_mfma_f32_16x16x32_bf16 v[138:141], v[106:109], v[186:189], v[138:141]
	v_mfma_f32_16x16x32_bf16 v[134:137], v[98:101], v[194:197], v[134:137]
	v_mfma_f32_16x16x32_bf16 v[130:133], v[106:109], v[194:197], v[130:133]
	v_mfma_f32_16x16x32_bf16 v[158:161], v[102:105], v[118:121], v[158:161]
	v_mfma_f32_16x16x32_bf16 v[154:157], v[110:113], v[118:121], v[154:157]
	v_mfma_f32_16x16x32_bf16 v[150:153], v[102:105], v[126:129], v[150:153]
	v_mfma_f32_16x16x32_bf16 v[146:149], v[110:113], v[126:129], v[146:149]
	v_mfma_f32_16x16x32_bf16 v[142:145], v[102:105], v[190:193], v[142:145]
	v_mfma_f32_16x16x32_bf16 v[138:141], v[110:113], v[190:193], v[138:141]
	v_mfma_f32_16x16x32_bf16 v[134:137], v[102:105], v[198:201], v[134:137]
	v_mfma_f32_16x16x32_bf16 v[130:133], v[110:113], v[198:201], v[130:133]
	v_mfma_f32_16x16x32_bf16 v[62:65], v[226:229], v[114:117], v[62:65]
	v_mfma_f32_16x16x32_bf16 v[58:61], v[234:237], v[114:117], v[58:61]
	v_mfma_f32_16x16x32_bf16 v[54:57], v[226:229], v[122:125], v[54:57]
	v_mfma_f32_16x16x32_bf16 v[50:53], v[234:237], v[122:125], v[50:53]
	v_mfma_f32_16x16x32_bf16 v[46:49], v[226:229], v[186:189], v[46:49]
	v_mfma_f32_16x16x32_bf16 v[42:45], v[234:237], v[186:189], v[42:45]
	v_mfma_f32_16x16x32_bf16 v[38:41], v[226:229], v[194:197], v[38:41]
	v_mfma_f32_16x16x32_bf16 v[34:37], v[234:237], v[194:197], v[34:37]
	v_mfma_f32_16x16x32_bf16 v[62:65], v[230:233], v[118:121], v[62:65]
	v_mfma_f32_16x16x32_bf16 v[58:61], v[242:245], v[118:121], v[58:61]
	v_mfma_f32_16x16x32_bf16 v[54:57], v[230:233], v[126:129], v[54:57]
	v_mfma_f32_16x16x32_bf16 v[50:53], v[242:245], v[126:129], v[50:53]
	v_mfma_f32_16x16x32_bf16 v[46:49], v[230:233], v[190:193], v[46:49]
	v_mfma_f32_16x16x32_bf16 v[42:45], v[242:245], v[190:193], v[42:45]
	v_mfma_f32_16x16x32_bf16 v[38:41], v[230:233], v[198:201], v[38:41]
	v_mfma_f32_16x16x32_bf16 v[34:37], v[242:245], v[198:201], v[34:37]
	s_mov_b32 m0, s85
	v_lshl_add_u64 v[248:249], s[48:49], 0, v[162:163]
	s_barrier
	ds_read_b128 v[114:117], v184 offset:16384
	ds_read_b128 v[118:121], v184 offset:17408
	ds_read_b128 v[122:125], v184 offset:18432
	ds_read_b128 v[126:129], v184 offset:19456
	ds_read_b128 v[186:189], v184 offset:20480
	ds_read_b128 v[190:193], v184 offset:21504
	ds_read_b128 v[194:197], v184 offset:22528
	ds_read_b128 v[198:201], v184 offset:23552
	global_load_lds_dwordx4 v[248:249], off
	v_lshl_add_u64 v[250:251], s[48:49], 0, v[164:165]
	s_mov_b32 m0, s82
	s_nop 0
	global_load_lds_dwordx4 v[250:251], off
	v_lshl_add_u64 v[174:175], s[2:3], 0, v[0:1]
	s_mov_b32 m0, s12
	v_lshl_add_u64 v[246:247], s[2:3], 0, v[166:167]
	global_load_lds_dwordx4 v[174:175], off
	s_add_i32 m0, s12, 0x2000
	s_nop 0
	global_load_lds_dwordx4 v[246:247], off
	s_add_u32 s12, s2, 0x40000
	s_addc_u32 s13, s3, 0
	s_add_i32 s54, s54, s78
	v_lshl_add_u64 v[174:175], s[12:13], 0, v[0:1]
	s_mov_b32 m0, s54
	s_nop 0
	global_load_lds_dwordx4 v[174:175], off
	v_lshl_add_u64 v[174:175], s[12:13], 0, v[166:167]
	s_add_i32 m0, s54, 0x2000
	s_nop 0
	global_load_lds_dwordx4 v[174:175], off
	s_waitcnt vmcnt(6)
	s_barrier
	s_waitcnt lgkmcnt(0)
	v_mfma_f32_16x16x32_bf16 v[94:97], v[98:101], v[114:117], v[94:97]
	v_mfma_f32_16x16x32_bf16 v[90:93], v[106:109], v[114:117], v[90:93]
	v_mfma_f32_16x16x32_bf16 v[86:89], v[98:101], v[122:125], v[86:89]
	v_mfma_f32_16x16x32_bf16 v[82:85], v[106:109], v[122:125], v[82:85]
	v_mfma_f32_16x16x32_bf16 v[78:81], v[98:101], v[186:189], v[78:81]
	v_mfma_f32_16x16x32_bf16 v[74:77], v[106:109], v[186:189], v[74:77]
	v_mfma_f32_16x16x32_bf16 v[70:73], v[98:101], v[194:197], v[70:73]
	v_mfma_f32_16x16x32_bf16 v[66:69], v[106:109], v[194:197], v[66:69]
	v_mfma_f32_16x16x32_bf16 v[94:97], v[102:105], v[118:121], v[94:97]
	v_mfma_f32_16x16x32_bf16 v[90:93], v[110:113], v[118:121], v[90:93]
	v_mfma_f32_16x16x32_bf16 v[86:89], v[102:105], v[126:129], v[86:89]
	v_mfma_f32_16x16x32_bf16 v[82:85], v[110:113], v[126:129], v[82:85]
	v_mfma_f32_16x16x32_bf16 v[78:81], v[102:105], v[190:193], v[78:81]
	v_mfma_f32_16x16x32_bf16 v[74:77], v[110:113], v[190:193], v[74:77]
	v_mfma_f32_16x16x32_bf16 v[70:73], v[102:105], v[198:201], v[70:73]
	v_mfma_f32_16x16x32_bf16 v[66:69], v[110:113], v[198:201], v[66:69]
	v_mfma_f32_16x16x32_bf16 v[30:33], v[226:229], v[114:117], v[30:33]
	v_mfma_f32_16x16x32_bf16 v[26:29], v[234:237], v[114:117], v[26:29]
	v_mfma_f32_16x16x32_bf16 v[22:25], v[226:229], v[122:125], v[22:25]
	v_mfma_f32_16x16x32_bf16 v[18:21], v[234:237], v[122:125], v[18:21]
	v_mfma_f32_16x16x32_bf16 v[14:17], v[226:229], v[186:189], v[14:17]
	v_mfma_f32_16x16x32_bf16 v[10:13], v[234:237], v[186:189], v[10:13]
	v_mfma_f32_16x16x32_bf16 v[6:9], v[226:229], v[194:197], v[6:9]
	v_mfma_f32_16x16x32_bf16 v[2:5], v[234:237], v[194:197], v[2:5]
	v_mfma_f32_16x16x32_bf16 v[30:33], v[230:233], v[118:121], v[30:33]
	v_mfma_f32_16x16x32_bf16 v[26:29], v[242:245], v[118:121], v[26:29]
	v_mfma_f32_16x16x32_bf16 v[22:25], v[230:233], v[126:129], v[22:25]
	v_mfma_f32_16x16x32_bf16 v[18:21], v[242:245], v[126:129], v[18:21]
	v_mfma_f32_16x16x32_bf16 v[14:17], v[230:233], v[190:193], v[14:17]
	v_mfma_f32_16x16x32_bf16 v[10:13], v[242:245], v[190:193], v[10:13]
	v_mfma_f32_16x16x32_bf16 v[6:9], v[230:233], v[198:201], v[6:9]
	v_mfma_f32_16x16x32_bf16 v[2:5], v[242:245], v[198:201], v[2:5]
	s_add_i32 s54, 0, 0x18000
	v_add_u32_e32 v110, s54, v179
	s_barrier
	ds_read_b128 v[98:101], v110
	ds_read_b128 v[102:105], v110 offset:1024
	ds_read_b128 v[106:109], v110 offset:2048
	ds_read_b128 v[110:113], v110 offset:3072
	s_add_u32 s12, s48, 0x3e000
	s_addc_u32 s13, s49, 0
	s_mov_b32 m0, s89
	v_lshl_add_u64 v[226:227], s[12:13], 0, v[162:163]
	ds_read_b128 v[114:117], v184 offset:32768
	ds_read_b128 v[118:121], v184 offset:33792
	ds_read_b128 v[122:125], v184 offset:34816
	ds_read_b128 v[126:129], v184 offset:35840
	ds_read_b128 v[186:189], v184 offset:36864
	ds_read_b128 v[190:193], v184 offset:37888
	ds_read_b128 v[194:197], v184 offset:38912
	ds_read_b128 v[198:201], v184 offset:39936
	global_load_lds_dwordx4 v[226:227], off
	v_lshl_add_u64 v[226:227], s[12:13], 0, v[164:165]
	s_mov_b32 m0, s91
	s_nop 0
	global_load_lds_dwordx4 v[226:227], off
	s_waitcnt lgkmcnt(8)
	s_add_i32 s12, 0, 0x1c000
	s_add_i32 s13, s54, s78
	v_add_u32_e32 v242, s12, v179
	ds_read_b128 v[226:229], v242
	ds_read_b128 v[230:233], v242 offset:1024
	ds_read_b128 v[234:237], v242 offset:2048
	ds_read_b128 v[242:245], v242 offset:3072
	s_barrier
	s_waitcnt lgkmcnt(0)
	s_nop 0
	v_mfma_f32_16x16x32_bf16 v[158:161], v[98:101], v[114:117], v[158:161]
	v_mfma_f32_16x16x32_bf16 v[154:157], v[106:109], v[114:117], v[154:157]
	v_mfma_f32_16x16x32_bf16 v[150:153], v[98:101], v[122:125], v[150:153]
	v_mfma_f32_16x16x32_bf16 v[146:149], v[106:109], v[122:125], v[146:149]
	v_mfma_f32_16x16x32_bf16 v[142:145], v[98:101], v[186:189], v[142:145]
	v_mfma_f32_16x16x32_bf16 v[138:141], v[106:109], v[186:189], v[138:141]
	v_mfma_f32_16x16x32_bf16 v[134:137], v[98:101], v[194:197], v[134:137]
	v_mfma_f32_16x16x32_bf16 v[130:133], v[106:109], v[194:197], v[130:133]
	v_mfma_f32_16x16x32_bf16 v[158:161], v[102:105], v[118:121], v[158:161]
	v_mfma_f32_16x16x32_bf16 v[154:157], v[110:113], v[118:121], v[154:157]
	v_mfma_f32_16x16x32_bf16 v[150:153], v[102:105], v[126:129], v[150:153]
	v_mfma_f32_16x16x32_bf16 v[146:149], v[110:113], v[126:129], v[146:149]
	v_mfma_f32_16x16x32_bf16 v[142:145], v[102:105], v[190:193], v[142:145]
	v_mfma_f32_16x16x32_bf16 v[138:141], v[110:113], v[190:193], v[138:141]
	v_mfma_f32_16x16x32_bf16 v[134:137], v[102:105], v[198:201], v[134:137]
	v_mfma_f32_16x16x32_bf16 v[130:133], v[110:113], v[198:201], v[130:133]
	v_mfma_f32_16x16x32_bf16 v[62:65], v[226:229], v[114:117], v[62:65]
	v_mfma_f32_16x16x32_bf16 v[58:61], v[234:237], v[114:117], v[58:61]
	v_mfma_f32_16x16x32_bf16 v[54:57], v[226:229], v[122:125], v[54:57]
	v_mfma_f32_16x16x32_bf16 v[50:53], v[234:237], v[122:125], v[50:53]
	v_mfma_f32_16x16x32_bf16 v[46:49], v[226:229], v[186:189], v[46:49]
	v_mfma_f32_16x16x32_bf16 v[42:45], v[234:237], v[186:189], v[42:45]
	v_mfma_f32_16x16x32_bf16 v[38:41], v[226:229], v[194:197], v[38:41]
	v_mfma_f32_16x16x32_bf16 v[34:37], v[234:237], v[194:197], v[34:37]
	v_mfma_f32_16x16x32_bf16 v[62:65], v[230:233], v[118:121], v[62:65]
	v_mfma_f32_16x16x32_bf16 v[58:61], v[242:245], v[118:121], v[58:61]
	v_mfma_f32_16x16x32_bf16 v[54:57], v[230:233], v[126:129], v[54:57]
	v_mfma_f32_16x16x32_bf16 v[50:53], v[242:245], v[126:129], v[50:53]
	v_mfma_f32_16x16x32_bf16 v[46:49], v[230:233], v[190:193], v[46:49]
	v_mfma_f32_16x16x32_bf16 v[42:45], v[242:245], v[190:193], v[42:45]
	v_mfma_f32_16x16x32_bf16 v[38:41], v[230:233], v[198:201], v[38:41]
	v_mfma_f32_16x16x32_bf16 v[34:37], v[242:245], v[198:201], v[34:37]
	s_mov_b32 m0, s79
	v_lshl_add_u64 v[174:175], v[248:249], 0, s[20:21]
	s_barrier
	ds_read_b128 v[114:117], v184 offset:49152
	ds_read_b128 v[118:121], v184 offset:50176
	ds_read_b128 v[122:125], v184 offset:51200
	ds_read_b128 v[126:129], v184 offset:52224
	ds_read_b128 v[186:189], v184 offset:53248
	ds_read_b128 v[190:193], v184 offset:54272
	ds_read_b128 v[194:197], v184 offset:55296
	ds_read_b128 v[198:201], v184 offset:56320
	global_load_lds_dwordx4 v[174:175], off
	v_lshl_add_u64 v[174:175], v[250:251], 0, s[20:21]
	s_mov_b32 m0, s87
	s_nop 0
	global_load_lds_dwordx4 v[174:175], off
	v_lshl_add_u64 v[174:175], s[2:3], 0, v[0:1]
	v_lshl_add_u64 v[174:175], v[174:175], 0, s[20:21]
	s_mov_b32 m0, s13
	s_nop 0
	global_load_lds_dwordx4 v[174:175], off
	v_lshl_add_u64 v[174:175], v[246:247], 0, s[20:21]
	s_add_i32 m0, s13, 0x2000
	s_nop 0
	global_load_lds_dwordx4 v[174:175], off
	s_add_u32 s2, s2, 0x40080
	s_addc_u32 s3, s3, 0
	s_add_i32 s12, s12, s78
	v_lshl_add_u64 v[174:175], s[2:3], 0, v[0:1]
	s_mov_b32 m0, s12
	s_nop 0
	global_load_lds_dwordx4 v[174:175], off
	v_lshl_add_u64 v[174:175], s[2:3], 0, v[166:167]
	s_add_i32 m0, s12, 0x2000
	s_nop 0
	global_load_lds_dwordx4 v[174:175], off
	s_waitcnt vmcnt(6)
	s_barrier
	s_waitcnt lgkmcnt(0)
	s_nop 0
	v_mfma_f32_16x16x32_bf16 v[94:97], v[98:101], v[114:117], v[94:97]
	v_mfma_f32_16x16x32_bf16 v[90:93], v[106:109], v[114:117], v[90:93]
	v_mfma_f32_16x16x32_bf16 v[86:89], v[98:101], v[122:125], v[86:89]
	v_mfma_f32_16x16x32_bf16 v[82:85], v[106:109], v[122:125], v[82:85]
	v_mfma_f32_16x16x32_bf16 v[78:81], v[98:101], v[186:189], v[78:81]
	v_mfma_f32_16x16x32_bf16 v[74:77], v[106:109], v[186:189], v[74:77]
	v_mfma_f32_16x16x32_bf16 v[70:73], v[98:101], v[194:197], v[70:73]
	v_mfma_f32_16x16x32_bf16 v[66:69], v[106:109], v[194:197], v[66:69]
	v_mfma_f32_16x16x32_bf16 v[94:97], v[102:105], v[118:121], v[94:97]
	v_mfma_f32_16x16x32_bf16 v[90:93], v[110:113], v[118:121], v[90:93]
	v_mfma_f32_16x16x32_bf16 v[86:89], v[102:105], v[126:129], v[86:89]
	v_mfma_f32_16x16x32_bf16 v[82:85], v[110:113], v[126:129], v[82:85]
	v_mfma_f32_16x16x32_bf16 v[78:81], v[102:105], v[190:193], v[78:81]
	v_mfma_f32_16x16x32_bf16 v[74:77], v[110:113], v[190:193], v[74:77]
	v_mfma_f32_16x16x32_bf16 v[70:73], v[102:105], v[198:201], v[70:73]
	v_mfma_f32_16x16x32_bf16 v[66:69], v[110:113], v[198:201], v[66:69]
	v_mfma_f32_16x16x32_bf16 v[30:33], v[226:229], v[114:117], v[30:33]
	v_mfma_f32_16x16x32_bf16 v[26:29], v[234:237], v[114:117], v[26:29]
	v_mfma_f32_16x16x32_bf16 v[22:25], v[226:229], v[122:125], v[22:25]
	v_mfma_f32_16x16x32_bf16 v[18:21], v[234:237], v[122:125], v[18:21]
	v_mfma_f32_16x16x32_bf16 v[14:17], v[226:229], v[186:189], v[14:17]
	v_mfma_f32_16x16x32_bf16 v[10:13], v[234:237], v[186:189], v[10:13]
	v_mfma_f32_16x16x32_bf16 v[6:9], v[226:229], v[194:197], v[6:9]
	v_mfma_f32_16x16x32_bf16 v[2:5], v[234:237], v[194:197], v[2:5]
	v_mfma_f32_16x16x32_bf16 v[30:33], v[230:233], v[118:121], v[30:33]
	v_mfma_f32_16x16x32_bf16 v[26:29], v[242:245], v[118:121], v[26:29]
	v_mfma_f32_16x16x32_bf16 v[22:25], v[230:233], v[126:129], v[22:25]
	v_mfma_f32_16x16x32_bf16 v[18:21], v[242:245], v[126:129], v[18:21]
	v_mfma_f32_16x16x32_bf16 v[14:17], v[230:233], v[190:193], v[14:17]
	v_mfma_f32_16x16x32_bf16 v[10:13], v[242:245], v[190:193], v[10:13]
	v_mfma_f32_16x16x32_bf16 v[6:9], v[230:233], v[198:201], v[6:9]
	v_mfma_f32_16x16x32_bf16 v[2:5], v[242:245], v[198:201], v[2:5]
	s_add_i32 s53, s53, 2
	s_add_u32 s34, s34, 0x100
	s_addc_u32 s35, s35, 0
	s_add_u32 s51, s51, 0x100
	s_addc_u32 s52, s52, 0
	s_cmp_gt_u32 s53, 13
	s_barrier
	s_cbranch_scc0 .LBB0_104

.LBB0_181:
	s_add_i32 s88, s44, -2
	s_add_u32 s34, s34, 0x80
	s_addc_u32 s35, s35, 0
	s_add_u32 s89, s42, 0x100
	v_mov_b32_e32 v2, 0
	s_addc_u32 s90, s43, 0
	s_mov_b32 s2, 0
	s_add_i32 s91, s2, 2
	s_add_u32 s12, s34, 0x80
	s_addc_u32 s3, s35, 0
	s_add_i32 s13, 0, 0x10000
	v_add_u32_e32 v142, s13, v183
	ds_read_b128 v[130:133], v142
	ds_read_b128 v[134:137], v142 offset:1024
	ds_read_b128 v[138:141], v142 offset:2048
	ds_read_b128 v[142:145], v142 offset:3072
	s_cmp_eq_u32 s88, s2
	s_cselect_b32 s2, s0, s12
	s_cselect_b32 s3, s1, s3
	s_cselect_b32 s43, s41, s90
	s_cselect_b32 s42, s40, s89
	v_lshl_add_u64 v[190:191], s[34:35], 0, v[174:175]
	s_add_i32 m0, s55, 0xc000
	ds_read_b128 v[146:149], v184
	ds_read_b128 v[150:153], v184 offset:1024
	ds_read_b128 v[154:157], v184 offset:2048
	ds_read_b128 v[158:161], v184 offset:3072
	ds_read_b128 v[162:165], v184 offset:4096
	ds_read_b128 v[166:169], v184 offset:5120
	ds_read_b128 v[178:181], v184 offset:6144
	ds_read_b128 v[186:189], v184 offset:7168
	global_load_lds_dwordx4 v[190:191], off
	v_lshl_add_u64 v[190:191], s[34:35], 0, v[176:177]
	s_add_i32 m0, s55, 0xe000
	s_nop 0
	global_load_lds_dwordx4 v[190:191], off
	s_waitcnt lgkmcnt(8)
	s_add_i32 s92, 0, 0x14000
	s_add_i32 s12, s13, s54
	v_add_u32_e32 v185, s92, v183
	ds_read_b128 v[190:193], v185
	ds_read_b128 v[194:197], v185 offset:1024
	ds_read_b128 v[198:201], v185 offset:2048
	ds_read_b128 v[226:229], v185 offset:3072
	s_barrier
	s_waitcnt lgkmcnt(0)
	v_mfma_f32_16x16x32_bf16 v[126:129], v[130:133], v[146:149], 0
	v_mfma_f32_16x16x32_bf16 v[122:125], v[138:141], v[146:149], 0
	v_mfma_f32_16x16x32_bf16 v[118:121], v[130:133], v[154:157], 0
	v_mfma_f32_16x16x32_bf16 v[114:117], v[138:141], v[154:157], 0
	v_mfma_f32_16x16x32_bf16 v[110:113], v[130:133], v[162:165], 0
	v_mfma_f32_16x16x32_bf16 v[106:109], v[138:141], v[162:165], 0
	v_mfma_f32_16x16x32_bf16 v[102:105], v[130:133], v[178:181], 0
	v_mfma_f32_16x16x32_bf16 v[98:101], v[138:141], v[178:181], 0
	v_mfma_f32_16x16x32_bf16 v[126:129], v[134:137], v[150:153], v[126:129]
	v_mfma_f32_16x16x32_bf16 v[122:125], v[142:145], v[150:153], v[122:125]
	v_mfma_f32_16x16x32_bf16 v[118:121], v[134:137], v[158:161], v[118:121]
	v_mfma_f32_16x16x32_bf16 v[114:117], v[142:145], v[158:161], v[114:117]
	v_mfma_f32_16x16x32_bf16 v[110:113], v[134:137], v[166:169], v[110:113]
	v_mfma_f32_16x16x32_bf16 v[106:109], v[142:145], v[166:169], v[106:109]
	v_mfma_f32_16x16x32_bf16 v[102:105], v[134:137], v[186:189], v[102:105]
	v_mfma_f32_16x16x32_bf16 v[98:101], v[142:145], v[186:189], v[98:101]
	v_mfma_f32_16x16x32_bf16 v[62:65], v[190:193], v[146:149], 0
	v_mfma_f32_16x16x32_bf16 v[58:61], v[198:201], v[146:149], 0
	v_mfma_f32_16x16x32_bf16 v[54:57], v[190:193], v[154:157], 0
	v_mfma_f32_16x16x32_bf16 v[50:53], v[198:201], v[154:157], 0
	v_mfma_f32_16x16x32_bf16 v[46:49], v[190:193], v[162:165], 0
	v_mfma_f32_16x16x32_bf16 v[42:45], v[198:201], v[162:165], 0
	v_mfma_f32_16x16x32_bf16 v[38:41], v[190:193], v[178:181], 0
	v_mfma_f32_16x16x32_bf16 v[34:37], v[198:201], v[178:181], 0
	v_mfma_f32_16x16x32_bf16 v[62:65], v[194:197], v[150:153], v[62:65]
	v_mfma_f32_16x16x32_bf16 v[58:61], v[226:229], v[150:153], v[58:61]
	v_mfma_f32_16x16x32_bf16 v[54:57], v[194:197], v[158:161], v[54:57]
	v_mfma_f32_16x16x32_bf16 v[50:53], v[226:229], v[158:161], v[50:53]
	v_mfma_f32_16x16x32_bf16 v[46:49], v[194:197], v[166:169], v[46:49]
	v_mfma_f32_16x16x32_bf16 v[42:45], v[226:229], v[166:169], v[42:45]
	v_mfma_f32_16x16x32_bf16 v[38:41], v[194:197], v[186:189], v[38:41]
	v_mfma_f32_16x16x32_bf16 v[34:37], v[226:229], v[186:189], v[34:37]
	s_mov_b32 m0, s55
	v_lshl_add_u64 v[234:235], s[2:3], 0, v[170:171]
	s_barrier
	ds_read_b128 v[146:149], v184 offset:16384
	ds_read_b128 v[150:153], v184 offset:17408
	ds_read_b128 v[154:157], v184 offset:18432
	ds_read_b128 v[158:161], v184 offset:19456
	ds_read_b128 v[162:165], v184 offset:20480
	ds_read_b128 v[166:169], v184 offset:21504
	ds_read_b128 v[178:181], v184 offset:22528
	ds_read_b128 v[186:189], v184 offset:23552
	global_load_lds_dwordx4 v[234:235], off
	v_lshl_add_u64 v[236:237], s[2:3], 0, v[172:173]
	s_mov_b32 m0, s58
	s_nop 0
	global_load_lds_dwordx4 v[236:237], off
	v_lshl_add_u64 v[230:231], s[42:43], 0, v[170:171]
	s_mov_b32 m0, s12
	s_nop 0
	global_load_lds_dwordx4 v[230:231], off
	v_lshl_add_u64 v[232:233], s[42:43], 0, v[172:173]
	s_add_i32 m0, s12, 0x2000
	s_nop 0
	global_load_lds_dwordx4 v[232:233], off
	s_add_u32 s12, s42, s18
	s_addc_u32 s13, s43, 0
	s_add_i32 s42, s92, s54
	v_lshl_add_u64 v[242:243], s[12:13], 0, v[170:171]
	s_mov_b32 m0, s42
	v_lshl_add_u64 v[244:245], s[12:13], 0, v[172:173]
	global_load_lds_dwordx4 v[242:243], off
	s_add_i32 m0, s42, 0x2000
	s_nop 0
	global_load_lds_dwordx4 v[244:245], off
	s_waitcnt vmcnt(6)
	s_barrier
	s_waitcnt lgkmcnt(0)
	s_nop 0
	v_mfma_f32_16x16x32_bf16 v[94:97], v[130:133], v[146:149], 0
	v_mfma_f32_16x16x32_bf16 v[90:93], v[138:141], v[146:149], 0
	v_mfma_f32_16x16x32_bf16 v[86:89], v[130:133], v[154:157], 0
	v_mfma_f32_16x16x32_bf16 v[82:85], v[138:141], v[154:157], 0
	v_mfma_f32_16x16x32_bf16 v[78:81], v[130:133], v[162:165], 0
	v_mfma_f32_16x16x32_bf16 v[74:77], v[138:141], v[162:165], 0
	v_mfma_f32_16x16x32_bf16 v[70:73], v[130:133], v[178:181], 0
	v_mfma_f32_16x16x32_bf16 v[66:69], v[138:141], v[178:181], 0
	v_mfma_f32_16x16x32_bf16 v[94:97], v[134:137], v[150:153], v[94:97]
	v_mfma_f32_16x16x32_bf16 v[90:93], v[142:145], v[150:153], v[90:93]
	v_mfma_f32_16x16x32_bf16 v[86:89], v[134:137], v[158:161], v[86:89]
	v_mfma_f32_16x16x32_bf16 v[82:85], v[142:145], v[158:161], v[82:85]
	v_mfma_f32_16x16x32_bf16 v[78:81], v[134:137], v[166:169], v[78:81]
	v_mfma_f32_16x16x32_bf16 v[74:77], v[142:145], v[166:169], v[74:77]
	v_mfma_f32_16x16x32_bf16 v[70:73], v[134:137], v[186:189], v[70:73]
	v_mfma_f32_16x16x32_bf16 v[66:69], v[142:145], v[186:189], v[66:69]
	v_mfma_f32_16x16x32_bf16 v[30:33], v[190:193], v[146:149], 0
	v_mfma_f32_16x16x32_bf16 v[26:29], v[198:201], v[146:149], 0
	v_mfma_f32_16x16x32_bf16 v[22:25], v[190:193], v[154:157], 0
	v_mfma_f32_16x16x32_bf16 v[18:21], v[198:201], v[154:157], 0
	v_mfma_f32_16x16x32_bf16 v[14:17], v[190:193], v[162:165], 0
	v_mfma_f32_16x16x32_bf16 v[10:13], v[198:201], v[162:165], 0
	v_mfma_f32_16x16x32_bf16 v[6:9], v[190:193], v[178:181], 0
	v_mfma_f32_16x16x32_bf16 v[2:5], v[198:201], v[178:181], 0
	v_mfma_f32_16x16x32_bf16 v[30:33], v[194:197], v[150:153], v[30:33]
	v_mfma_f32_16x16x32_bf16 v[26:29], v[226:229], v[150:153], v[26:29]
	v_mfma_f32_16x16x32_bf16 v[22:25], v[194:197], v[158:161], v[22:25]
	v_mfma_f32_16x16x32_bf16 v[18:21], v[226:229], v[158:161], v[18:21]
	v_mfma_f32_16x16x32_bf16 v[14:17], v[194:197], v[166:169], v[14:17]
	v_mfma_f32_16x16x32_bf16 v[10:13], v[226:229], v[166:169], v[10:13]
	v_mfma_f32_16x16x32_bf16 v[6:9], v[194:197], v[186:189], v[6:9]
	v_mfma_f32_16x16x32_bf16 v[2:5], v[226:229], v[186:189], v[2:5]
	s_add_i32 s12, 0, 0x18000
	v_add_u32_e32 v142, s12, v183
	s_barrier
	ds_read_b128 v[130:133], v142
	ds_read_b128 v[134:137], v142 offset:1024
	ds_read_b128 v[138:141], v142 offset:2048
	ds_read_b128 v[142:145], v142 offset:3072
	s_add_u32 s2, s2, s18
	s_addc_u32 s3, s3, 0
	s_mov_b32 m0, s59
	v_lshl_add_u64 v[190:191], s[2:3], 0, v[170:171]
	ds_read_b128 v[146:149], v184 offset:32768
	ds_read_b128 v[150:153], v184 offset:33792
	ds_read_b128 v[154:157], v184 offset:34816
	ds_read_b128 v[158:161], v184 offset:35840
	ds_read_b128 v[162:165], v184 offset:36864
	ds_read_b128 v[166:169], v184 offset:37888
	ds_read_b128 v[178:181], v184 offset:38912
	ds_read_b128 v[186:189], v184 offset:39936
	global_load_lds_dwordx4 v[190:191], off
	v_lshl_add_u64 v[190:191], s[2:3], 0, v[172:173]
	s_mov_b32 m0, s77
	s_nop 0
	global_load_lds_dwordx4 v[190:191], off
	s_waitcnt lgkmcnt(8)
	s_add_i32 s2, 0, 0x1c000
	s_add_i32 s3, s12, s54
	v_add_u32_e32 v185, s2, v183
	ds_read_b128 v[190:193], v185
	ds_read_b128 v[194:197], v185 offset:1024
	ds_read_b128 v[198:201], v185 offset:2048
	ds_read_b128 v[226:229], v185 offset:3072
	s_barrier
	s_waitcnt lgkmcnt(0)
	v_mfma_f32_16x16x32_bf16 v[126:129], v[130:133], v[146:149], v[126:129]
	v_mfma_f32_16x16x32_bf16 v[122:125], v[138:141], v[146:149], v[122:125]
	v_mfma_f32_16x16x32_bf16 v[118:121], v[130:133], v[154:157], v[118:121]
	v_mfma_f32_16x16x32_bf16 v[114:117], v[138:141], v[154:157], v[114:117]
	v_mfma_f32_16x16x32_bf16 v[110:113], v[130:133], v[162:165], v[110:113]
	v_mfma_f32_16x16x32_bf16 v[106:109], v[138:141], v[162:165], v[106:109]
	v_mfma_f32_16x16x32_bf16 v[102:105], v[130:133], v[178:181], v[102:105]
	v_mfma_f32_16x16x32_bf16 v[98:101], v[138:141], v[178:181], v[98:101]
	v_mfma_f32_16x16x32_bf16 v[126:129], v[134:137], v[150:153], v[126:129]
	v_mfma_f32_16x16x32_bf16 v[122:125], v[142:145], v[150:153], v[122:125]
	v_mfma_f32_16x16x32_bf16 v[118:121], v[134:137], v[158:161], v[118:121]
	v_mfma_f32_16x16x32_bf16 v[114:117], v[142:145], v[158:161], v[114:117]
	v_mfma_f32_16x16x32_bf16 v[110:113], v[134:137], v[166:169], v[110:113]
	v_mfma_f32_16x16x32_bf16 v[106:109], v[142:145], v[166:169], v[106:109]
	v_mfma_f32_16x16x32_bf16 v[102:105], v[134:137], v[186:189], v[102:105]
	v_mfma_f32_16x16x32_bf16 v[98:101], v[142:145], v[186:189], v[98:101]
	v_mfma_f32_16x16x32_bf16 v[62:65], v[190:193], v[146:149], v[62:65]
	v_mfma_f32_16x16x32_bf16 v[58:61], v[198:201], v[146:149], v[58:61]
	v_mfma_f32_16x16x32_bf16 v[54:57], v[190:193], v[154:157], v[54:57]
	v_mfma_f32_16x16x32_bf16 v[50:53], v[198:201], v[154:157], v[50:53]
	v_mfma_f32_16x16x32_bf16 v[46:49], v[190:193], v[162:165], v[46:49]
	v_mfma_f32_16x16x32_bf16 v[42:45], v[198:201], v[162:165], v[42:45]
	v_mfma_f32_16x16x32_bf16 v[38:41], v[190:193], v[178:181], v[38:41]
	v_mfma_f32_16x16x32_bf16 v[34:37], v[198:201], v[178:181], v[34:37]
	v_mfma_f32_16x16x32_bf16 v[62:65], v[194:197], v[150:153], v[62:65]
	v_mfma_f32_16x16x32_bf16 v[58:61], v[226:229], v[150:153], v[58:61]
	v_mfma_f32_16x16x32_bf16 v[54:57], v[194:197], v[158:161], v[54:57]
	v_mfma_f32_16x16x32_bf16 v[50:53], v[226:229], v[158:161], v[50:53]
	v_mfma_f32_16x16x32_bf16 v[46:49], v[194:197], v[166:169], v[46:49]
	v_mfma_f32_16x16x32_bf16 v[42:45], v[226:229], v[166:169], v[42:45]
	v_mfma_f32_16x16x32_bf16 v[38:41], v[194:197], v[186:189], v[38:41]
	v_mfma_f32_16x16x32_bf16 v[34:37], v[226:229], v[186:189], v[34:37]
	s_mov_b32 m0, s80
	v_lshl_add_u64 v[234:235], v[234:235], 0, s[20:21]
	s_barrier
	ds_read_b128 v[146:149], v184 offset:49152
	ds_read_b128 v[150:153], v184 offset:50176
	ds_read_b128 v[154:157], v184 offset:51200
	ds_read_b128 v[158:161], v184 offset:52224
	ds_read_b128 v[162:165], v184 offset:53248
	ds_read_b128 v[166:169], v184 offset:54272
	ds_read_b128 v[178:181], v184 offset:55296
	ds_read_b128 v[186:189], v184 offset:56320
	global_load_lds_dwordx4 v[234:235], off
	v_lshl_add_u64 v[236:237], v[236:237], 0, s[20:21]
	s_mov_b32 m0, s81
	s_nop 0
	global_load_lds_dwordx4 v[236:237], off
	v_lshl_add_u64 v[230:231], v[230:231], 0, s[20:21]
	s_mov_b32 m0, s3
	s_nop 0
	global_load_lds_dwordx4 v[230:231], off
	v_lshl_add_u64 v[230:231], v[232:233], 0, s[20:21]
	s_add_i32 m0, s3, 0x2000
	s_nop 0
	global_load_lds_dwordx4 v[230:231], off
	s_add_i32 s2, s2, s54
	v_lshl_add_u64 v[242:243], v[242:243], 0, s[20:21]
	s_mov_b32 m0, s2
	s_nop 0
	global_load_lds_dwordx4 v[242:243], off
	v_lshl_add_u64 v[244:245], v[244:245], 0, s[20:21]
	s_add_i32 m0, s2, 0x2000
	s_nop 0
	global_load_lds_dwordx4 v[244:245], off
	s_waitcnt vmcnt(6)
	s_barrier
	s_waitcnt lgkmcnt(0)
	v_mfma_f32_16x16x32_bf16 v[94:97], v[130:133], v[146:149], v[94:97]
	v_mfma_f32_16x16x32_bf16 v[90:93], v[138:141], v[146:149], v[90:93]
	v_mfma_f32_16x16x32_bf16 v[86:89], v[130:133], v[154:157], v[86:89]
	v_mfma_f32_16x16x32_bf16 v[82:85], v[138:141], v[154:157], v[82:85]
	v_mfma_f32_16x16x32_bf16 v[78:81], v[130:133], v[162:165], v[78:81]
	v_mfma_f32_16x16x32_bf16 v[74:77], v[138:141], v[162:165], v[74:77]
	v_mfma_f32_16x16x32_bf16 v[70:73], v[130:133], v[178:181], v[70:73]
	v_mfma_f32_16x16x32_bf16 v[66:69], v[138:141], v[178:181], v[66:69]
	v_mfma_f32_16x16x32_bf16 v[94:97], v[134:137], v[150:153], v[94:97]
	v_mfma_f32_16x16x32_bf16 v[90:93], v[142:145], v[150:153], v[90:93]
	v_mfma_f32_16x16x32_bf16 v[86:89], v[134:137], v[158:161], v[86:89]
	v_mfma_f32_16x16x32_bf16 v[82:85], v[142:145], v[158:161], v[82:85]
	v_mfma_f32_16x16x32_bf16 v[78:81], v[134:137], v[166:169], v[78:81]
	v_mfma_f32_16x16x32_bf16 v[74:77], v[142:145], v[166:169], v[74:77]
	v_mfma_f32_16x16x32_bf16 v[70:73], v[134:137], v[186:189], v[70:73]
	v_mfma_f32_16x16x32_bf16 v[66:69], v[142:145], v[186:189], v[66:69]
	v_mfma_f32_16x16x32_bf16 v[30:33], v[190:193], v[146:149], v[30:33]
	v_mfma_f32_16x16x32_bf16 v[26:29], v[198:201], v[146:149], v[26:29]
	v_mfma_f32_16x16x32_bf16 v[22:25], v[190:193], v[154:157], v[22:25]
	v_mfma_f32_16x16x32_bf16 v[18:21], v[198:201], v[154:157], v[18:21]
	v_mfma_f32_16x16x32_bf16 v[14:17], v[190:193], v[162:165], v[14:17]
	v_mfma_f32_16x16x32_bf16 v[10:13], v[198:201], v[162:165], v[10:13]
	v_mfma_f32_16x16x32_bf16 v[6:9], v[190:193], v[178:181], v[6:9]
	v_mfma_f32_16x16x32_bf16 v[2:5], v[198:201], v[178:181], v[2:5]
	v_mfma_f32_16x16x32_bf16 v[30:33], v[194:197], v[150:153], v[30:33]
	v_mfma_f32_16x16x32_bf16 v[26:29], v[226:229], v[150:153], v[26:29]
	v_mfma_f32_16x16x32_bf16 v[22:25], v[194:197], v[158:161], v[22:25]
	v_mfma_f32_16x16x32_bf16 v[18:21], v[226:229], v[158:161], v[18:21]
	v_mfma_f32_16x16x32_bf16 v[14:17], v[194:197], v[166:169], v[14:17]
	v_mfma_f32_16x16x32_bf16 v[10:13], v[226:229], v[166:169], v[10:13]
	v_mfma_f32_16x16x32_bf16 v[6:9], v[194:197], v[186:189], v[6:9]
	v_mfma_f32_16x16x32_bf16 v[2:5], v[226:229], v[186:189], v[2:5]
	s_add_u32 s34, s34, 0x100
	s_addc_u32 s35, s35, 0
	s_add_u32 s89, s89, 0x100
	s_addc_u32 s90, s90, 0
	s_cmp_ge_i32 s91, s44
	s_mov_b32 s2, s91
	s_barrier
	s_cbranch_scc1 .Lpeel_x_1
.LBB0_182:
	s_add_i32 s91, s2, 2
	s_add_u32 s12, s34, 0x80
	s_addc_u32 s3, s35, 0
	s_add_i32 s13, 0, 0x10000
	v_add_u32_e32 v142, s13, v183
	ds_read_b128 v[130:133], v142
	ds_read_b128 v[134:137], v142 offset:1024
	ds_read_b128 v[138:141], v142 offset:2048
	ds_read_b128 v[142:145], v142 offset:3072
	s_cmp_eq_u32 s88, s2
	s_cselect_b32 s2, s0, s12
	s_cselect_b32 s3, s1, s3
	s_cselect_b32 s43, s41, s90
	s_cselect_b32 s42, s40, s89
	v_lshl_add_u64 v[190:191], s[34:35], 0, v[174:175]
	s_add_i32 m0, s55, 0xc000
	ds_read_b128 v[146:149], v184
	ds_read_b128 v[150:153], v184 offset:1024
	ds_read_b128 v[154:157], v184 offset:2048
	ds_read_b128 v[158:161], v184 offset:3072
	ds_read_b128 v[162:165], v184 offset:4096
	ds_read_b128 v[166:169], v184 offset:5120
	ds_read_b128 v[178:181], v184 offset:6144
	ds_read_b128 v[186:189], v184 offset:7168
	global_load_lds_dwordx4 v[190:191], off
	v_lshl_add_u64 v[190:191], s[34:35], 0, v[176:177]
	s_add_i32 m0, s55, 0xe000
	s_nop 0
	global_load_lds_dwordx4 v[190:191], off
	s_waitcnt lgkmcnt(8)
	s_add_i32 s92, 0, 0x14000
	s_add_i32 s12, s13, s54
	v_add_u32_e32 v185, s92, v183
	ds_read_b128 v[190:193], v185
	ds_read_b128 v[194:197], v185 offset:1024
	ds_read_b128 v[198:201], v185 offset:2048
	ds_read_b128 v[226:229], v185 offset:3072
	s_barrier
	s_waitcnt lgkmcnt(0)
	v_mfma_f32_16x16x32_bf16 v[126:129], v[130:133], v[146:149], v[126:129]
	v_mfma_f32_16x16x32_bf16 v[122:125], v[138:141], v[146:149], v[122:125]
	v_mfma_f32_16x16x32_bf16 v[118:121], v[130:133], v[154:157], v[118:121]
	v_mfma_f32_16x16x32_bf16 v[114:117], v[138:141], v[154:157], v[114:117]
	v_mfma_f32_16x16x32_bf16 v[110:113], v[130:133], v[162:165], v[110:113]
	v_mfma_f32_16x16x32_bf16 v[106:109], v[138:141], v[162:165], v[106:109]
	v_mfma_f32_16x16x32_bf16 v[102:105], v[130:133], v[178:181], v[102:105]
	v_mfma_f32_16x16x32_bf16 v[98:101], v[138:141], v[178:181], v[98:101]
	v_mfma_f32_16x16x32_bf16 v[126:129], v[134:137], v[150:153], v[126:129]
	v_mfma_f32_16x16x32_bf16 v[122:125], v[142:145], v[150:153], v[122:125]
	v_mfma_f32_16x16x32_bf16 v[118:121], v[134:137], v[158:161], v[118:121]
	v_mfma_f32_16x16x32_bf16 v[114:117], v[142:145], v[158:161], v[114:117]
	v_mfma_f32_16x16x32_bf16 v[110:113], v[134:137], v[166:169], v[110:113]
	v_mfma_f32_16x16x32_bf16 v[106:109], v[142:145], v[166:169], v[106:109]
	v_mfma_f32_16x16x32_bf16 v[102:105], v[134:137], v[186:189], v[102:105]
	v_mfma_f32_16x16x32_bf16 v[98:101], v[142:145], v[186:189], v[98:101]
	v_mfma_f32_16x16x32_bf16 v[62:65], v[190:193], v[146:149], v[62:65]
	v_mfma_f32_16x16x32_bf16 v[58:61], v[198:201], v[146:149], v[58:61]
	v_mfma_f32_16x16x32_bf16 v[54:57], v[190:193], v[154:157], v[54:57]
	v_mfma_f32_16x16x32_bf16 v[50:53], v[198:201], v[154:157], v[50:53]
	v_mfma_f32_16x16x32_bf16 v[46:49], v[190:193], v[162:165], v[46:49]
	v_mfma_f32_16x16x32_bf16 v[42:45], v[198:201], v[162:165], v[42:45]
	v_mfma_f32_16x16x32_bf16 v[38:41], v[190:193], v[178:181], v[38:41]
	v_mfma_f32_16x16x32_bf16 v[34:37], v[198:201], v[178:181], v[34:37]
	v_mfma_f32_16x16x32_bf16 v[62:65], v[194:197], v[150:153], v[62:65]
	v_mfma_f32_16x16x32_bf16 v[58:61], v[226:229], v[150:153], v[58:61]
	v_mfma_f32_16x16x32_bf16 v[54:57], v[194:197], v[158:161], v[54:57]
	v_mfma_f32_16x16x32_bf16 v[50:53], v[226:229], v[158:161], v[50:53]
	v_mfma_f32_16x16x32_bf16 v[46:49], v[194:197], v[166:169], v[46:49]
	v_mfma_f32_16x16x32_bf16 v[42:45], v[226:229], v[166:169], v[42:45]
	v_mfma_f32_16x16x32_bf16 v[38:41], v[194:197], v[186:189], v[38:41]
	v_mfma_f32_16x16x32_bf16 v[34:37], v[226:229], v[186:189], v[34:37]
	s_mov_b32 m0, s55
	v_lshl_add_u64 v[234:235], s[2:3], 0, v[170:171]
	s_barrier
	ds_read_b128 v[146:149], v184 offset:16384
	ds_read_b128 v[150:153], v184 offset:17408
	ds_read_b128 v[154:157], v184 offset:18432
	ds_read_b128 v[158:161], v184 offset:19456
	ds_read_b128 v[162:165], v184 offset:20480
	ds_read_b128 v[166:169], v184 offset:21504
	ds_read_b128 v[178:181], v184 offset:22528
	ds_read_b128 v[186:189], v184 offset:23552
	global_load_lds_dwordx4 v[234:235], off
	v_lshl_add_u64 v[236:237], s[2:3], 0, v[172:173]
	s_mov_b32 m0, s58
	s_nop 0
	global_load_lds_dwordx4 v[236:237], off
	v_lshl_add_u64 v[230:231], s[42:43], 0, v[170:171]
	s_mov_b32 m0, s12
	s_nop 0
	global_load_lds_dwordx4 v[230:231], off
	v_lshl_add_u64 v[232:233], s[42:43], 0, v[172:173]
	s_add_i32 m0, s12, 0x2000
	s_nop 0
	global_load_lds_dwordx4 v[232:233], off
	s_add_u32 s12, s42, s18
	s_addc_u32 s13, s43, 0
	s_add_i32 s42, s92, s54
	v_lshl_add_u64 v[242:243], s[12:13], 0, v[170:171]
	s_mov_b32 m0, s42
	v_lshl_add_u64 v[244:245], s[12:13], 0, v[172:173]
	global_load_lds_dwordx4 v[242:243], off
	s_add_i32 m0, s42, 0x2000
	s_nop 0
	global_load_lds_dwordx4 v[244:245], off
	s_waitcnt vmcnt(6)
	s_barrier
	s_waitcnt lgkmcnt(0)
	s_nop 0
	v_mfma_f32_16x16x32_bf16 v[94:97], v[130:133], v[146:149], v[94:97]
	v_mfma_f32_16x16x32_bf16 v[90:93], v[138:141], v[146:149], v[90:93]
	v_mfma_f32_16x16x32_bf16 v[86:89], v[130:133], v[154:157], v[86:89]
	v_mfma_f32_16x16x32_bf16 v[82:85], v[138:141], v[154:157], v[82:85]
	v_mfma_f32_16x16x32_bf16 v[78:81], v[130:133], v[162:165], v[78:81]
	v_mfma_f32_16x16x32_bf16 v[74:77], v[138:141], v[162:165], v[74:77]
	v_mfma_f32_16x16x32_bf16 v[70:73], v[130:133], v[178:181], v[70:73]
	v_mfma_f32_16x16x32_bf16 v[66:69], v[138:141], v[178:181], v[66:69]
	v_mfma_f32_16x16x32_bf16 v[94:97], v[134:137], v[150:153], v[94:97]
	v_mfma_f32_16x16x32_bf16 v[90:93], v[142:145], v[150:153], v[90:93]
	v_mfma_f32_16x16x32_bf16 v[86:89], v[134:137], v[158:161], v[86:89]
	v_mfma_f32_16x16x32_bf16 v[82:85], v[142:145], v[158:161], v[82:85]
	v_mfma_f32_16x16x32_bf16 v[78:81], v[134:137], v[166:169], v[78:81]
	v_mfma_f32_16x16x32_bf16 v[74:77], v[142:145], v[166:169], v[74:77]
	v_mfma_f32_16x16x32_bf16 v[70:73], v[134:137], v[186:189], v[70:73]
	v_mfma_f32_16x16x32_bf16 v[66:69], v[142:145], v[186:189], v[66:69]
	v_mfma_f32_16x16x32_bf16 v[30:33], v[190:193], v[146:149], v[30:33]
	v_mfma_f32_16x16x32_bf16 v[26:29], v[198:201], v[146:149], v[26:29]
	v_mfma_f32_16x16x32_bf16 v[22:25], v[190:193], v[154:157], v[22:25]
	v_mfma_f32_16x16x32_bf16 v[18:21], v[198:201], v[154:157], v[18:21]
	v_mfma_f32_16x16x32_bf16 v[14:17], v[190:193], v[162:165], v[14:17]
	v_mfma_f32_16x16x32_bf16 v[10:13], v[198:201], v[162:165], v[10:13]
	v_mfma_f32_16x16x32_bf16 v[6:9], v[190:193], v[178:181], v[6:9]
	v_mfma_f32_16x16x32_bf16 v[2:5], v[198:201], v[178:181], v[2:5]
	v_mfma_f32_16x16x32_bf16 v[30:33], v[194:197], v[150:153], v[30:33]
	v_mfma_f32_16x16x32_bf16 v[26:29], v[226:229], v[150:153], v[26:29]
	v_mfma_f32_16x16x32_bf16 v[22:25], v[194:197], v[158:161], v[22:25]
	v_mfma_f32_16x16x32_bf16 v[18:21], v[226:229], v[158:161], v[18:21]
	v_mfma_f32_16x16x32_bf16 v[14:17], v[194:197], v[166:169], v[14:17]
	v_mfma_f32_16x16x32_bf16 v[10:13], v[226:229], v[166:169], v[10:13]
	v_mfma_f32_16x16x32_bf16 v[6:9], v[194:197], v[186:189], v[6:9]
	v_mfma_f32_16x16x32_bf16 v[2:5], v[226:229], v[186:189], v[2:5]
	s_add_i32 s12, 0, 0x18000
	v_add_u32_e32 v142, s12, v183
	s_barrier
	ds_read_b128 v[130:133], v142
	ds_read_b128 v[134:137], v142 offset:1024
	ds_read_b128 v[138:141], v142 offset:2048
	ds_read_b128 v[142:145], v142 offset:3072
	s_add_u32 s2, s2, s18
	s_addc_u32 s3, s3, 0
	s_mov_b32 m0, s59
	v_lshl_add_u64 v[190:191], s[2:3], 0, v[170:171]
	ds_read_b128 v[146:149], v184 offset:32768
	ds_read_b128 v[150:153], v184 offset:33792
	ds_read_b128 v[154:157], v184 offset:34816
	ds_read_b128 v[158:161], v184 offset:35840
	ds_read_b128 v[162:165], v184 offset:36864
	ds_read_b128 v[166:169], v184 offset:37888
	ds_read_b128 v[178:181], v184 offset:38912
	ds_read_b128 v[186:189], v184 offset:39936
	global_load_lds_dwordx4 v[190:191], off
	v_lshl_add_u64 v[190:191], s[2:3], 0, v[172:173]
	s_mov_b32 m0, s77
	s_nop 0
	global_load_lds_dwordx4 v[190:191], off
	s_waitcnt lgkmcnt(8)
	s_add_i32 s2, 0, 0x1c000
	s_add_i32 s3, s12, s54
	v_add_u32_e32 v185, s2, v183
	ds_read_b128 v[190:193], v185
	ds_read_b128 v[194:197], v185 offset:1024
	ds_read_b128 v[198:201], v185 offset:2048
	ds_read_b128 v[226:229], v185 offset:3072
	s_barrier
	s_waitcnt lgkmcnt(0)
	v_mfma_f32_16x16x32_bf16 v[126:129], v[130:133], v[146:149], v[126:129]
	v_mfma_f32_16x16x32_bf16 v[122:125], v[138:141], v[146:149], v[122:125]
	v_mfma_f32_16x16x32_bf16 v[118:121], v[130:133], v[154:157], v[118:121]
	v_mfma_f32_16x16x32_bf16 v[114:117], v[138:141], v[154:157], v[114:117]
	v_mfma_f32_16x16x32_bf16 v[110:113], v[130:133], v[162:165], v[110:113]
	v_mfma_f32_16x16x32_bf16 v[106:109], v[138:141], v[162:165], v[106:109]
	v_mfma_f32_16x16x32_bf16 v[102:105], v[130:133], v[178:181], v[102:105]
	v_mfma_f32_16x16x32_bf16 v[98:101], v[138:141], v[178:181], v[98:101]
	v_mfma_f32_16x16x32_bf16 v[126:129], v[134:137], v[150:153], v[126:129]
	v_mfma_f32_16x16x32_bf16 v[122:125], v[142:145], v[150:153], v[122:125]
	v_mfma_f32_16x16x32_bf16 v[118:121], v[134:137], v[158:161], v[118:121]
	v_mfma_f32_16x16x32_bf16 v[114:117], v[142:145], v[158:161], v[114:117]
	v_mfma_f32_16x16x32_bf16 v[110:113], v[134:137], v[166:169], v[110:113]
	v_mfma_f32_16x16x32_bf16 v[106:109], v[142:145], v[166:169], v[106:109]
	v_mfma_f32_16x16x32_bf16 v[102:105], v[134:137], v[186:189], v[102:105]
	v_mfma_f32_16x16x32_bf16 v[98:101], v[142:145], v[186:189], v[98:101]
	v_mfma_f32_16x16x32_bf16 v[62:65], v[190:193], v[146:149], v[62:65]
	v_mfma_f32_16x16x32_bf16 v[58:61], v[198:201], v[146:149], v[58:61]
	v_mfma_f32_16x16x32_bf16 v[54:57], v[190:193], v[154:157], v[54:57]
	v_mfma_f32_16x16x32_bf16 v[50:53], v[198:201], v[154:157], v[50:53]
	v_mfma_f32_16x16x32_bf16 v[46:49], v[190:193], v[162:165], v[46:49]
	v_mfma_f32_16x16x32_bf16 v[42:45], v[198:201], v[162:165], v[42:45]
	v_mfma_f32_16x16x32_bf16 v[38:41], v[190:193], v[178:181], v[38:41]
	v_mfma_f32_16x16x32_bf16 v[34:37], v[198:201], v[178:181], v[34:37]
	v_mfma_f32_16x16x32_bf16 v[62:65], v[194:197], v[150:153], v[62:65]
	v_mfma_f32_16x16x32_bf16 v[58:61], v[226:229], v[150:153], v[58:61]
	v_mfma_f32_16x16x32_bf16 v[54:57], v[194:197], v[158:161], v[54:57]
	v_mfma_f32_16x16x32_bf16 v[50:53], v[226:229], v[158:161], v[50:53]
	v_mfma_f32_16x16x32_bf16 v[46:49], v[194:197], v[166:169], v[46:49]
	v_mfma_f32_16x16x32_bf16 v[42:45], v[226:229], v[166:169], v[42:45]
	v_mfma_f32_16x16x32_bf16 v[38:41], v[194:197], v[186:189], v[38:41]
	v_mfma_f32_16x16x32_bf16 v[34:37], v[226:229], v[186:189], v[34:37]
	s_mov_b32 m0, s80
	v_lshl_add_u64 v[234:235], v[234:235], 0, s[20:21]
	s_barrier
	ds_read_b128 v[146:149], v184 offset:49152
	ds_read_b128 v[150:153], v184 offset:50176
	ds_read_b128 v[154:157], v184 offset:51200
	ds_read_b128 v[158:161], v184 offset:52224
	ds_read_b128 v[162:165], v184 offset:53248
	ds_read_b128 v[166:169], v184 offset:54272
	ds_read_b128 v[178:181], v184 offset:55296
	ds_read_b128 v[186:189], v184 offset:56320
	global_load_lds_dwordx4 v[234:235], off
	v_lshl_add_u64 v[236:237], v[236:237], 0, s[20:21]
	s_mov_b32 m0, s81
	s_nop 0
	global_load_lds_dwordx4 v[236:237], off
	v_lshl_add_u64 v[230:231], v[230:231], 0, s[20:21]
	s_mov_b32 m0, s3
	s_nop 0
	global_load_lds_dwordx4 v[230:231], off
	v_lshl_add_u64 v[230:231], v[232:233], 0, s[20:21]
	s_add_i32 m0, s3, 0x2000
	s_nop 0
	global_load_lds_dwordx4 v[230:231], off
	s_add_i32 s2, s2, s54
	v_lshl_add_u64 v[242:243], v[242:243], 0, s[20:21]
	s_mov_b32 m0, s2
	s_nop 0
	global_load_lds_dwordx4 v[242:243], off
	v_lshl_add_u64 v[244:245], v[244:245], 0, s[20:21]
	s_add_i32 m0, s2, 0x2000
	s_nop 0
	global_load_lds_dwordx4 v[244:245], off
	s_waitcnt vmcnt(6)
	s_barrier
	s_waitcnt lgkmcnt(0)
	v_mfma_f32_16x16x32_bf16 v[94:97], v[130:133], v[146:149], v[94:97]
	v_mfma_f32_16x16x32_bf16 v[90:93], v[138:141], v[146:149], v[90:93]
	v_mfma_f32_16x16x32_bf16 v[86:89], v[130:133], v[154:157], v[86:89]
	v_mfma_f32_16x16x32_bf16 v[82:85], v[138:141], v[154:157], v[82:85]
	v_mfma_f32_16x16x32_bf16 v[78:81], v[130:133], v[162:165], v[78:81]
	v_mfma_f32_16x16x32_bf16 v[74:77], v[138:141], v[162:165], v[74:77]
	v_mfma_f32_16x16x32_bf16 v[70:73], v[130:133], v[178:181], v[70:73]
	v_mfma_f32_16x16x32_bf16 v[66:69], v[138:141], v[178:181], v[66:69]
	v_mfma_f32_16x16x32_bf16 v[94:97], v[134:137], v[150:153], v[94:97]
	v_mfma_f32_16x16x32_bf16 v[90:93], v[142:145], v[150:153], v[90:93]
	v_mfma_f32_16x16x32_bf16 v[86:89], v[134:137], v[158:161], v[86:89]
	v_mfma_f32_16x16x32_bf16 v[82:85], v[142:145], v[158:161], v[82:85]
	v_mfma_f32_16x16x32_bf16 v[78:81], v[134:137], v[166:169], v[78:81]
	v_mfma_f32_16x16x32_bf16 v[74:77], v[142:145], v[166:169], v[74:77]
	v_mfma_f32_16x16x32_bf16 v[70:73], v[134:137], v[186:189], v[70:73]
	v_mfma_f32_16x16x32_bf16 v[66:69], v[142:145], v[186:189], v[66:69]
	v_mfma_f32_16x16x32_bf16 v[30:33], v[190:193], v[146:149], v[30:33]
	v_mfma_f32_16x16x32_bf16 v[26:29], v[198:201], v[146:149], v[26:29]
	v_mfma_f32_16x16x32_bf16 v[22:25], v[190:193], v[154:157], v[22:25]
	v_mfma_f32_16x16x32_bf16 v[18:21], v[198:201], v[154:157], v[18:21]
	v_mfma_f32_16x16x32_bf16 v[14:17], v[190:193], v[162:165], v[14:17]
	v_mfma_f32_16x16x32_bf16 v[10:13], v[198:201], v[162:165], v[10:13]
	v_mfma_f32_16x16x32_bf16 v[6:9], v[190:193], v[178:181], v[6:9]
	v_mfma_f32_16x16x32_bf16 v[2:5], v[198:201], v[178:181], v[2:5]
	v_mfma_f32_16x16x32_bf16 v[30:33], v[194:197], v[150:153], v[30:33]
	v_mfma_f32_16x16x32_bf16 v[26:29], v[226:229], v[150:153], v[26:29]
	v_mfma_f32_16x16x32_bf16 v[22:25], v[194:197], v[158:161], v[22:25]
	v_mfma_f32_16x16x32_bf16 v[18:21], v[226:229], v[158:161], v[18:21]
	v_mfma_f32_16x16x32_bf16 v[14:17], v[194:197], v[166:169], v[14:17]
	v_mfma_f32_16x16x32_bf16 v[10:13], v[226:229], v[166:169], v[10:13]
	v_mfma_f32_16x16x32_bf16 v[6:9], v[194:197], v[186:189], v[6:9]
	v_mfma_f32_16x16x32_bf16 v[2:5], v[226:229], v[186:189], v[2:5]
	s_add_u32 s34, s34, 0x100
	s_addc_u32 s35, s35, 0
	s_add_u32 s89, s89, 0x100
	s_addc_u32 s90, s90, 0
	s_cmp_ge_i32 s91, s44
	s_mov_b32 s2, s91
	s_barrier
	s_cbranch_scc0 .LBB0_182

.LBB0_366:
	s_add_u32 s2, s0, 0xfffc0080
	s_addc_u32 s3, s1, -1
	s_add_i32 s12, 0, 0x10000
	v_add_u32_e32 v142, s12, v227
	ds_read_b128 v[130:133], v142
	ds_read_b128 v[134:137], v142 offset:1024
	ds_read_b128 v[138:141], v142 offset:2048
	ds_read_b128 v[142:145], v142 offset:3072
	s_cmp_eq_u32 s47, 12
	s_cselect_b32 s17, s15, s3
	s_cselect_b32 s16, s19, s2
	s_cselect_b32 s3, s43, s46
	s_cselect_b32 s2, s44, s45
	v_lshl_add_u64 v[190:191], s[0:1], 0, v[162:163]
	s_add_i32 m0, s54, 0xc000
	ds_read_b128 v[146:149], v233
	ds_read_b128 v[150:153], v233 offset:1024
	ds_read_b128 v[166:169], v233 offset:2048
	ds_read_b128 v[170:173], v233 offset:3072
	ds_read_b128 v[174:177], v233 offset:4096
	ds_read_b128 v[178:181], v233 offset:5120
	ds_read_b128 v[182:185], v233 offset:6144
	ds_read_b128 v[186:189], v233 offset:7168
	global_load_lds_dwordx4 v[190:191], off
	v_lshl_add_u64 v[190:191], s[0:1], 0, v[164:165]
	s_add_i32 m0, s54, 0xe000
	s_nop 0
	global_load_lds_dwordx4 v[190:191], off
	s_waitcnt lgkmcnt(8)
	s_barrier
	s_waitcnt lgkmcnt(0)
	v_mfma_f32_16x16x32_bf16 v[126:129], v[130:133], v[146:149], v[126:129]
	v_mfma_f32_16x16x32_bf16 v[122:125], v[138:141], v[146:149], v[122:125]
	v_mfma_f32_16x16x32_bf16 v[118:121], v[130:133], v[166:169], v[118:121]
	v_mfma_f32_16x16x32_bf16 v[114:117], v[138:141], v[166:169], v[114:117]
	v_mfma_f32_16x16x32_bf16 v[110:113], v[130:133], v[174:177], v[110:113]
	v_mfma_f32_16x16x32_bf16 v[106:109], v[138:141], v[174:177], v[106:109]
	v_mfma_f32_16x16x32_bf16 v[102:105], v[130:133], v[182:185], v[102:105]
	v_mfma_f32_16x16x32_bf16 v[98:101], v[138:141], v[182:185], v[98:101]
	v_mfma_f32_16x16x32_bf16 v[126:129], v[134:137], v[150:153], v[126:129]
	v_mfma_f32_16x16x32_bf16 v[122:125], v[142:145], v[150:153], v[122:125]
	v_mfma_f32_16x16x32_bf16 v[118:121], v[134:137], v[170:173], v[118:121]
	v_mfma_f32_16x16x32_bf16 v[114:117], v[142:145], v[170:173], v[114:117]
	v_mfma_f32_16x16x32_bf16 v[110:113], v[134:137], v[178:181], v[110:113]
	v_mfma_f32_16x16x32_bf16 v[106:109], v[142:145], v[178:181], v[106:109]
	v_mfma_f32_16x16x32_bf16 v[102:105], v[134:137], v[186:189], v[102:105]
	v_mfma_f32_16x16x32_bf16 v[98:101], v[142:145], v[186:189], v[98:101]
	s_barrier
	s_add_i32 s13, 0, 0x14000
	s_add_i32 s12, s12, s35
	v_add_u32_e32 v234, s13, v227
	v_lshl_add_u64 v[242:243], s[2:3], 0, v[0:1]
	s_mov_b32 m0, s12
	ds_read_b128 v[190:193], v234
	ds_read_b128 v[194:197], v234 offset:1024
	ds_read_b128 v[198:201], v234 offset:2048
	ds_read_b128 v[234:237], v234 offset:3072
	global_load_lds_dwordx4 v[242:243], off
	v_lshl_add_u64 v[244:245], s[2:3], 0, v[154:155]
	s_add_i32 m0, s12, 0x2000
	s_nop 0
	global_load_lds_dwordx4 v[244:245], off
	s_barrier
	s_waitcnt lgkmcnt(0)
	s_nop 0
	v_mfma_f32_16x16x32_bf16 v[62:65], v[190:193], v[146:149], v[62:65]
	v_mfma_f32_16x16x32_bf16 v[58:61], v[198:201], v[146:149], v[58:61]
	v_mfma_f32_16x16x32_bf16 v[54:57], v[190:193], v[166:169], v[54:57]
	v_mfma_f32_16x16x32_bf16 v[50:53], v[198:201], v[166:169], v[50:53]
	v_mfma_f32_16x16x32_bf16 v[46:49], v[190:193], v[174:177], v[46:49]
	v_mfma_f32_16x16x32_bf16 v[42:45], v[198:201], v[174:177], v[42:45]
	v_mfma_f32_16x16x32_bf16 v[38:41], v[190:193], v[182:185], v[38:41]
	v_mfma_f32_16x16x32_bf16 v[34:37], v[198:201], v[182:185], v[34:37]
	v_mfma_f32_16x16x32_bf16 v[62:65], v[194:197], v[150:153], v[62:65]
	v_mfma_f32_16x16x32_bf16 v[58:61], v[234:237], v[150:153], v[58:61]
	v_mfma_f32_16x16x32_bf16 v[54:57], v[194:197], v[170:173], v[54:57]
	v_mfma_f32_16x16x32_bf16 v[50:53], v[234:237], v[170:173], v[50:53]
	v_mfma_f32_16x16x32_bf16 v[46:49], v[194:197], v[178:181], v[46:49]
	v_mfma_f32_16x16x32_bf16 v[42:45], v[234:237], v[178:181], v[42:45]
	v_mfma_f32_16x16x32_bf16 v[38:41], v[194:197], v[186:189], v[38:41]
	v_mfma_f32_16x16x32_bf16 v[34:37], v[234:237], v[186:189], v[34:37]
	s_mov_b32 m0, s54
	s_nop 0
	s_barrier
	ds_read_b128 v[146:149], v233 offset:16384
	ds_read_b128 v[150:153], v233 offset:17408
	ds_read_b128 v[166:169], v233 offset:18432
	ds_read_b128 v[170:173], v233 offset:19456
	ds_read_b128 v[174:177], v233 offset:20480
	ds_read_b128 v[178:181], v233 offset:21504
	ds_read_b128 v[182:185], v233 offset:22528
	ds_read_b128 v[186:189], v233 offset:23552
	global_load_lds_dwordx4 v250, s[16:17]
	s_nop 0
	s_mov_b32 m0, s55
	s_nop 0
	global_load_lds_dwordx4 v251, s[16:17]
	s_barrier
	s_waitcnt lgkmcnt(0)
	v_mfma_f32_16x16x32_bf16 v[94:97], v[130:133], v[146:149], v[94:97]
	v_mfma_f32_16x16x32_bf16 v[90:93], v[138:141], v[146:149], v[90:93]
	v_mfma_f32_16x16x32_bf16 v[86:89], v[130:133], v[166:169], v[86:89]
	v_mfma_f32_16x16x32_bf16 v[82:85], v[138:141], v[166:169], v[82:85]
	v_mfma_f32_16x16x32_bf16 v[78:81], v[130:133], v[174:177], v[78:81]
	v_mfma_f32_16x16x32_bf16 v[74:77], v[138:141], v[174:177], v[74:77]
	v_mfma_f32_16x16x32_bf16 v[70:73], v[130:133], v[182:185], v[70:73]
	v_mfma_f32_16x16x32_bf16 v[66:69], v[138:141], v[182:185], v[66:69]
	v_mfma_f32_16x16x32_bf16 v[94:97], v[134:137], v[150:153], v[94:97]
	v_mfma_f32_16x16x32_bf16 v[90:93], v[142:145], v[150:153], v[90:93]
	v_mfma_f32_16x16x32_bf16 v[86:89], v[134:137], v[170:173], v[86:89]
	v_mfma_f32_16x16x32_bf16 v[82:85], v[142:145], v[170:173], v[82:85]
	v_mfma_f32_16x16x32_bf16 v[78:81], v[134:137], v[178:181], v[78:81]
	v_mfma_f32_16x16x32_bf16 v[74:77], v[142:145], v[178:181], v[74:77]
	v_mfma_f32_16x16x32_bf16 v[70:73], v[134:137], v[186:189], v[70:73]
	v_mfma_f32_16x16x32_bf16 v[66:69], v[142:145], v[186:189], v[66:69]
	s_barrier
	s_add_u32 s78, s2, 0x40000
	s_addc_u32 s79, s3, 0
	s_add_i32 s12, s13, s35
	v_lshl_add_u64 v[130:131], s[78:79], 0, v[0:1]
	s_mov_b32 m0, s12
	s_nop 0
	global_load_lds_dwordx4 v[130:131], off
	v_lshl_add_u64 v[130:131], s[78:79], 0, v[154:155]
	s_add_i32 m0, s12, 0x2000
	s_nop 0
	global_load_lds_dwordx4 v[130:131], off
	s_waitcnt vmcnt(6)
	s_barrier
	v_mfma_f32_16x16x32_bf16 v[30:33], v[190:193], v[146:149], v[30:33]
	v_mfma_f32_16x16x32_bf16 v[26:29], v[198:201], v[146:149], v[26:29]
	v_mfma_f32_16x16x32_bf16 v[22:25], v[190:193], v[166:169], v[22:25]
	v_mfma_f32_16x16x32_bf16 v[18:21], v[198:201], v[166:169], v[18:21]
	v_mfma_f32_16x16x32_bf16 v[14:17], v[190:193], v[174:177], v[14:17]
	v_mfma_f32_16x16x32_bf16 v[10:13], v[198:201], v[174:177], v[10:13]
	v_mfma_f32_16x16x32_bf16 v[6:9], v[190:193], v[182:185], v[6:9]
	v_mfma_f32_16x16x32_bf16 v[2:5], v[198:201], v[182:185], v[2:5]
	v_mfma_f32_16x16x32_bf16 v[30:33], v[194:197], v[150:153], v[30:33]
	v_mfma_f32_16x16x32_bf16 v[26:29], v[234:237], v[150:153], v[26:29]
	v_mfma_f32_16x16x32_bf16 v[22:25], v[194:197], v[170:173], v[22:25]
	v_mfma_f32_16x16x32_bf16 v[18:21], v[234:237], v[170:173], v[18:21]
	v_mfma_f32_16x16x32_bf16 v[14:17], v[194:197], v[178:181], v[14:17]
	v_mfma_f32_16x16x32_bf16 v[10:13], v[234:237], v[178:181], v[10:13]
	v_mfma_f32_16x16x32_bf16 v[6:9], v[194:197], v[186:189], v[6:9]
	v_mfma_f32_16x16x32_bf16 v[2:5], v[234:237], v[186:189], v[2:5]
	s_add_i32 s12, 0, 0x18000
	v_add_u32_e32 v142, s12, v227
	s_barrier
	ds_read_b128 v[130:133], v142
	ds_read_b128 v[134:137], v142 offset:1024
	ds_read_b128 v[138:141], v142 offset:2048
	ds_read_b128 v[142:145], v142 offset:3072
	s_add_u32 s16, s16, 0x40000
	s_addc_u32 s17, s17, 0
	s_mov_b32 m0, s58
	s_nop 0
	ds_read_b128 v[146:149], v233 offset:32768
	ds_read_b128 v[150:153], v233 offset:33792
	ds_read_b128 v[166:169], v233 offset:34816
	ds_read_b128 v[170:173], v233 offset:35840
	ds_read_b128 v[174:177], v233 offset:36864
	ds_read_b128 v[178:181], v233 offset:37888
	ds_read_b128 v[182:185], v233 offset:38912
	ds_read_b128 v[186:189], v233 offset:39936
	global_load_lds_dwordx4 v250, s[16:17]
	s_nop 0
	s_mov_b32 m0, s59
	s_nop 0
	global_load_lds_dwordx4 v251, s[16:17]
	s_waitcnt lgkmcnt(8)
	s_barrier
	s_waitcnt lgkmcnt(0)
	s_nop 0
	v_mfma_f32_16x16x32_bf16 v[126:129], v[130:133], v[146:149], v[126:129]
	v_mfma_f32_16x16x32_bf16 v[122:125], v[138:141], v[146:149], v[122:125]
	v_mfma_f32_16x16x32_bf16 v[118:121], v[130:133], v[166:169], v[118:121]
	v_mfma_f32_16x16x32_bf16 v[114:117], v[138:141], v[166:169], v[114:117]
	v_mfma_f32_16x16x32_bf16 v[110:113], v[130:133], v[174:177], v[110:113]
	v_mfma_f32_16x16x32_bf16 v[106:109], v[138:141], v[174:177], v[106:109]
	v_mfma_f32_16x16x32_bf16 v[102:105], v[130:133], v[182:185], v[102:105]
	v_mfma_f32_16x16x32_bf16 v[98:101], v[138:141], v[182:185], v[98:101]
	v_mfma_f32_16x16x32_bf16 v[126:129], v[134:137], v[150:153], v[126:129]
	v_mfma_f32_16x16x32_bf16 v[122:125], v[142:145], v[150:153], v[122:125]
	v_mfma_f32_16x16x32_bf16 v[118:121], v[134:137], v[170:173], v[118:121]
	v_mfma_f32_16x16x32_bf16 v[114:117], v[142:145], v[170:173], v[114:117]
	v_mfma_f32_16x16x32_bf16 v[110:113], v[134:137], v[178:181], v[110:113]
	v_mfma_f32_16x16x32_bf16 v[106:109], v[142:145], v[178:181], v[106:109]
	v_mfma_f32_16x16x32_bf16 v[102:105], v[134:137], v[186:189], v[102:105]
	v_mfma_f32_16x16x32_bf16 v[98:101], v[142:145], v[186:189], v[98:101]
	s_barrier
	s_add_i32 s13, 0, 0x1c000
	s_add_i32 s12, s12, s35
	v_add_u32_e32 v234, s13, v227
	v_lshl_add_u64 v[242:243], v[242:243], 0, s[20:21]
	s_mov_b32 m0, s12
	ds_read_b128 v[190:193], v234
	ds_read_b128 v[194:197], v234 offset:1024
	ds_read_b128 v[198:201], v234 offset:2048
	ds_read_b128 v[234:237], v234 offset:3072
	global_load_lds_dwordx4 v[242:243], off
	v_lshl_add_u64 v[242:243], v[244:245], 0, s[20:21]
	s_add_i32 m0, s12, 0x2000
	s_nop 0
	global_load_lds_dwordx4 v[242:243], off
	s_barrier
	s_waitcnt lgkmcnt(0)
	s_nop 0
	v_mfma_f32_16x16x32_bf16 v[62:65], v[190:193], v[146:149], v[62:65]
	v_mfma_f32_16x16x32_bf16 v[58:61], v[198:201], v[146:149], v[58:61]
	v_mfma_f32_16x16x32_bf16 v[54:57], v[190:193], v[166:169], v[54:57]
	v_mfma_f32_16x16x32_bf16 v[50:53], v[198:201], v[166:169], v[50:53]
	v_mfma_f32_16x16x32_bf16 v[46:49], v[190:193], v[174:177], v[46:49]
	v_mfma_f32_16x16x32_bf16 v[42:45], v[198:201], v[174:177], v[42:45]
	v_mfma_f32_16x16x32_bf16 v[38:41], v[190:193], v[182:185], v[38:41]
	v_mfma_f32_16x16x32_bf16 v[34:37], v[198:201], v[182:185], v[34:37]
	v_mfma_f32_16x16x32_bf16 v[62:65], v[194:197], v[150:153], v[62:65]
	v_mfma_f32_16x16x32_bf16 v[58:61], v[234:237], v[150:153], v[58:61]
	v_mfma_f32_16x16x32_bf16 v[54:57], v[194:197], v[170:173], v[54:57]
	v_mfma_f32_16x16x32_bf16 v[50:53], v[234:237], v[170:173], v[50:53]
	v_mfma_f32_16x16x32_bf16 v[46:49], v[194:197], v[178:181], v[46:49]
	v_mfma_f32_16x16x32_bf16 v[42:45], v[234:237], v[178:181], v[42:45]
	v_mfma_f32_16x16x32_bf16 v[38:41], v[194:197], v[186:189], v[38:41]
	v_mfma_f32_16x16x32_bf16 v[34:37], v[234:237], v[186:189], v[34:37]
	s_mov_b32 m0, s96
	s_add_u32 s78, s16, 0xfffc0080
	s_addc_u32 s79, s17, -1
	s_barrier
	ds_read_b128 v[146:149], v233 offset:49152
	ds_read_b128 v[150:153], v233 offset:50176
	ds_read_b128 v[166:169], v233 offset:51200
	ds_read_b128 v[170:173], v233 offset:52224
	ds_read_b128 v[174:177], v233 offset:53248
	ds_read_b128 v[178:181], v233 offset:54272
	ds_read_b128 v[182:185], v233 offset:55296
	ds_read_b128 v[186:189], v233 offset:56320
	global_load_lds_dwordx4 v250, s[78:79]
	s_nop 0
	s_mov_b32 m0, s97
	s_nop 0
	global_load_lds_dwordx4 v251, s[78:79]
	s_barrier
	s_waitcnt lgkmcnt(0)
	v_mfma_f32_16x16x32_bf16 v[94:97], v[130:133], v[146:149], v[94:97]
	v_mfma_f32_16x16x32_bf16 v[90:93], v[138:141], v[146:149], v[90:93]
	v_mfma_f32_16x16x32_bf16 v[86:89], v[130:133], v[166:169], v[86:89]
	v_mfma_f32_16x16x32_bf16 v[82:85], v[138:141], v[166:169], v[82:85]
	v_mfma_f32_16x16x32_bf16 v[78:81], v[130:133], v[174:177], v[78:81]
	v_mfma_f32_16x16x32_bf16 v[74:77], v[138:141], v[174:177], v[74:77]
	v_mfma_f32_16x16x32_bf16 v[70:73], v[130:133], v[182:185], v[70:73]
	v_mfma_f32_16x16x32_bf16 v[66:69], v[138:141], v[182:185], v[66:69]
	v_mfma_f32_16x16x32_bf16 v[94:97], v[134:137], v[150:153], v[94:97]
	v_mfma_f32_16x16x32_bf16 v[90:93], v[142:145], v[150:153], v[90:93]
	v_mfma_f32_16x16x32_bf16 v[86:89], v[134:137], v[170:173], v[86:89]
	v_mfma_f32_16x16x32_bf16 v[82:85], v[142:145], v[170:173], v[82:85]
	v_mfma_f32_16x16x32_bf16 v[78:81], v[134:137], v[178:181], v[78:81]
	v_mfma_f32_16x16x32_bf16 v[74:77], v[142:145], v[178:181], v[74:77]
	v_mfma_f32_16x16x32_bf16 v[70:73], v[134:137], v[186:189], v[70:73]
	v_mfma_f32_16x16x32_bf16 v[66:69], v[142:145], v[186:189], v[66:69]
	s_barrier
	s_add_u32 s2, s2, 0x40080
	s_addc_u32 s3, s3, 0
	s_add_i32 s12, s13, s35
	v_lshl_add_u64 v[130:131], s[2:3], 0, v[0:1]
	s_mov_b32 m0, s12
	s_nop 0
	global_load_lds_dwordx4 v[130:131], off
	v_lshl_add_u64 v[130:131], s[2:3], 0, v[154:155]
	s_add_i32 m0, s12, 0x2000
	s_nop 0
	global_load_lds_dwordx4 v[130:131], off
	s_waitcnt vmcnt(6)
	s_barrier
	v_mfma_f32_16x16x32_bf16 v[30:33], v[190:193], v[146:149], v[30:33]
	v_mfma_f32_16x16x32_bf16 v[26:29], v[198:201], v[146:149], v[26:29]
	v_mfma_f32_16x16x32_bf16 v[22:25], v[190:193], v[166:169], v[22:25]
	v_mfma_f32_16x16x32_bf16 v[18:21], v[198:201], v[166:169], v[18:21]
	v_mfma_f32_16x16x32_bf16 v[14:17], v[190:193], v[174:177], v[14:17]
	v_mfma_f32_16x16x32_bf16 v[10:13], v[198:201], v[174:177], v[10:13]
	v_mfma_f32_16x16x32_bf16 v[6:9], v[190:193], v[182:185], v[6:9]
	v_mfma_f32_16x16x32_bf16 v[2:5], v[198:201], v[182:185], v[2:5]
	v_mfma_f32_16x16x32_bf16 v[30:33], v[194:197], v[150:153], v[30:33]
	v_mfma_f32_16x16x32_bf16 v[26:29], v[234:237], v[150:153], v[26:29]
	v_mfma_f32_16x16x32_bf16 v[22:25], v[194:197], v[170:173], v[22:25]
	v_mfma_f32_16x16x32_bf16 v[18:21], v[234:237], v[170:173], v[18:21]
	v_mfma_f32_16x16x32_bf16 v[14:17], v[194:197], v[178:181], v[14:17]
	v_mfma_f32_16x16x32_bf16 v[10:13], v[234:237], v[178:181], v[10:13]
	v_mfma_f32_16x16x32_bf16 v[6:9], v[194:197], v[186:189], v[6:9]
	v_mfma_f32_16x16x32_bf16 v[2:5], v[234:237], v[186:189], v[2:5]
	s_add_i32 s47, s47, 2
	s_add_u32 s0, s0, 0x100
	s_addc_u32 s1, s1, 0
	s_add_u32 s45, s45, 0x100
	s_addc_u32 s46, s46, 0
	s_cmp_gt_u32 s47, 13
	s_barrier
	s_cbranch_scc0 .LBB0_366
